# GEMM tile prologue de-serialised: stage-1 early DMA pieces requested before waiting for stage 0 (buffer 1 is free after the previous epilogue barrier)
# baseline (speedup 1.0000x reference)
; template <int EPI, int MI>
; DI void gemm_tile(const GemmDesc& g, int tm, int tn, char* smem) {
;     ...
;   const int tid = get_tid(), lane = tid & 63, wave = tid >> 6, r = lane & 31, hh = lane >> 5;
;   const int wm = wave >> 1, wn = wave & 1;
;   const int m0 = tm * BM, n0 = tn * 128;
;   const int nk = g.K >> 6;
;   f32x16 acc[MI][2];
; #pragma unroll
;   for (int a = 0; a < MI; ++a)
; #pragma unroll
;     for (int b = 0; b < 2; ++b)
; #pragma unroll
;       for (int i = 0; i < 16; ++i) acc[a][b][i] = 0.f;
;   const int srow = tid >> 3;
;   const int schunk = (tid & 7) ^ ((srow & 7) ^ ((srow >> 3) & 3));
;     ...
;   const int rowA = wm * (32 * MI) + r, rowB = wn * 64 + r;
;   const int hk = hh ^ ((r & 7) ^ ((r >> 3) & 3));
;     ...
;   G_GLDS(0, 0);
;   asm volatile("s_waitcnt vmcnt(0)" ::: "memory");
;   __syncthreads();
; template <int EPI, int MI>
; DI void gemm_phase(const GemmDesc& g, char* smem, int vb, int nvb) {
;     ...
;   for (int q = start; q < local; q += step) {
;     const int mg = q / per;
;     const int rem = q - mg * per;
;     const int tn = rem / PM;
;     const int tm = mbase + mg * PM + (rem - tn * PM);
.LBB0_202:
	s_abs_i32 s1, s5
	v_readlane_b32 s15, v219, 45
	s_mul_hi_u32 s15, s1, s15
	v_readlane_b32 s18, v219, 44
	s_mul_i32 s16, s15, s18
	s_sub_i32 s1, s1, s16
	s_ashr_i32 s0, s5, 31
	s_add_i32 s16, s15, 1
	s_sub_i32 s17, s1, s18
	s_cmp_ge_u32 s1, s18
	s_cselect_b32 s15, s16, s15
	s_cselect_b32 s1, s17, s1
	s_add_i32 s16, s15, 1
	s_cmp_ge_u32 s1, s18
	s_cselect_b32 s1, s16, s15
	s_xor_b32 s1, s1, s0
	s_sub_i32 s15, s1, s0
	s_mul_i32 s16, s15, s18
	s_sub_i32 s16, s5, s16
	s_abs_i32 s18, s16
	v_readlane_b32 s19, v219, 46
	s_mul_hi_u32 s19, s18, s19
	v_readlane_b32 s42, v218, 32
	s_mul_i32 s38, s19, s42
	s_sub_i32 s18, s18, s38
	s_ashr_i32 s17, s16, 31
	s_add_i32 s38, s19, 1
	s_sub_i32 s39, s18, s42
	s_cmp_ge_u32 s18, s42
	s_cselect_b32 s19, s38, s19
	s_cselect_b32 s18, s39, s18
	s_add_i32 s38, s19, 1
	s_cmp_ge_u32 s18, s42
	s_cselect_b32 s18, s38, s19
	s_xor_b32 s18, s18, s17
	s_sub_i32 s39, s18, s17
	s_sub_i32 s15, s15, s39
	v_mov_b32_e32 v4, v132
	s_mul_i32 s15, s15, s42
	s_add_i32 s16, s16, s54
	s_add_i32 s38, s16, s15
	v_ashrrev_i32_e32 v97, 3, v4
	v_ashrrev_i32_e32 v120, 7, v4
	v_bfe_u32 v0, v4, 6, 2
	v_xor_b32_e32 v1, v97, v4
	s_mulk_i32 s38, 0xc0
	v_and_b32_e32 v121, 31, v4
	v_bitop3_b32 v2, v1, v0, 7 bitop3:0x6c
	v_mul_lo_u32 v0, v120, s6
	v_and_b32_e32 v115, 7, v4
	v_or_b32_e32 v5, v0, v121
	v_lshrrev_b32_e32 v0, 3, v4
	s_waitcnt vmcnt(10)
	v_add_u32_e32 v98, s38, v97
	v_bfe_u32 v122, v4, 5, 1
	v_bitop3_b32 v0, v0, v115, 3 bitop3:0x6c
	v_ashrrev_i32_e32 v99, 31, v98
	v_xor_b32_e32 v6, v0, v122
	v_lshlrev_b64 v[0:1], 11, v[98:99]
	v_readlane_b32 s42, v223, 59
	v_lshlrev_b32_e32 v99, 4, v4
	v_readlane_b32 s43, v223, 60
	v_lshlrev_b32_e32 v100, 4, v2
	v_lshl_add_u32 v2, s39, 7, v97
	v_add_u32_e32 v124, 0, v99
	v_lshl_add_u64 v[0:1], s[42:43], 0, v[0:1]
	v_mov_b32_e32 v101, v96
	v_ashrrev_i32_e32 v3, 31, v2
	v_readfirstlane_b32 s15, v124
	v_add_u32_e32 v125, 0x1000, v124
	v_lshl_add_u64 v[0:1], v[0:1], 0, v[100:101]
	v_lshlrev_b64 v[2:3], 11, v[2:3]
	s_mov_b32 m0, s15
	s_mov_b64 s[42:43], 0x10000
	v_readfirstlane_b32 s15, v125
	v_add_u32_e32 v126, 0x2000, v124
	s_waitcnt vmcnt(9)
	v_lshl_add_u64 v[102:103], s[70:71], 0, v[2:3]
	global_load_lds_dwordx4 v[0:1], off
	v_lshl_add_u64 v[2:3], v[0:1], 0, s[42:43]
	s_mov_b32 m0, s15
	s_mov_b64 s[44:45], 0x20000
	v_readfirstlane_b32 s15, v126
	v_add_u32_e32 v127, 0x3000, v124
	global_load_lds_dwordx4 v[2:3], off
	v_lshl_add_u64 v[2:3], v[0:1], 0, s[44:45]
	s_mov_b32 m0, s15
	s_mov_b64 s[46:47], 0x30000
	v_readfirstlane_b32 s15, v127
	v_add_u32_e32 v128, 0x4000, v124
	global_load_lds_dwordx4 v[2:3], off
	v_lshl_add_u64 v[2:3], v[0:1], 0, s[46:47]
	s_mov_b32 m0, s15
	s_mov_b64 s[52:53], 0x40000
	v_readfirstlane_b32 s15, v128
	v_add_u32_e32 v129, 0x5000, v124
	global_load_lds_dwordx4 v[2:3], off
	v_lshl_add_u64 v[2:3], v[0:1], 0, s[52:53]
	s_mov_b32 m0, s15
	s_mov_b64 s[52:53], 0x50000
	v_readfirstlane_b32 s15, v129
	v_add_u32_e32 v130, 0xc000, v124
	global_load_lds_dwordx4 v[2:3], off
	v_lshl_add_u64 v[0:1], v[0:1], 0, s[52:53]
	s_mov_b32 m0, s15
	v_readfirstlane_b32 s15, v130
	v_add_u32_e32 v131, 0xd000, v124
	global_load_lds_dwordx4 v[0:1], off
	v_lshl_add_u64 v[0:1], v[102:103], 0, v[100:101]
	s_mov_b32 m0, s15
	v_readfirstlane_b32 s15, v131
	v_add_u32_e32 v153, 0xe000, v124
	global_load_lds_dwordx4 v[0:1], off
	v_lshl_add_u64 v[2:3], v[0:1], 0, s[42:43]
	s_mov_b32 m0, s15
	v_readfirstlane_b32 s15, v153
	v_add_u32_e32 v154, 0xf000, v124
	global_load_lds_dwordx4 v[2:3], off
	v_lshl_add_u64 v[2:3], v[0:1], 0, s[44:45]
	s_mov_b32 m0, s15
	v_readfirstlane_b32 s15, v154
	global_load_lds_dwordx4 v[2:3], off
	v_lshl_add_u64 v[0:1], v[0:1], 0, s[46:47]
	s_mov_b32 m0, s15
	s_mul_i32 s0, s0, 43
	global_load_lds_dwordx4 v[0:1], off
	s_add_i32 s17, s17, s0
	s_sub_i32 s0, s17, s18
	s_mul_i32 s1, s1, 43
	s_sub_i32 s0, s0, s1
	v_readlane_b32 s1, v218, 33
	v_bfe_u32 v123, v4, 6, 1
	v_lshlrev_b32_e32 v0, 7, v121
	s_mul_i32 s0, s1, s0
	v_lshl_or_b32 v0, v123, 13, v0
	s_add_i32 s0, s0, s4
	v_add_u32_e32 v156, 0, v0
	v_add_u32_e32 v158, s10, v0
	v_add_u32_e32 v0, s0, v97
	v_ashrrev_i32_e32 v1, 31, v0
	s_waitcnt vmcnt(0)
; template <int EPI, int MI>
; DI void gemm_tile(const GemmDesc& g, int tm, int tn, char* smem) {
;     ...
;   f32x16 acc[MI][2];
; #pragma unroll
;   for (int a = 0; a < MI; ++a)
; #pragma unroll
;     for (int b = 0; b < 2; ++b)
; #pragma unroll
;       for (int i = 0; i < 16; ++i) acc[a][b][i] = 0.f;
;   const int srow = tid >> 3;
;   const int schunk = (tid & 7) ^ ((srow & 7) ^ ((srow >> 3) & 3));
;     ...
;   const int rowA = wm * (32 * MI) + r, rowB = wn * 64 + r;
;   const int hk = hh ^ ((r & 7) ^ ((r >> 3) & 3));
;     ...
;   G_GLDS(0, 0);
;   asm volatile("s_waitcnt vmcnt(0)" ::: "memory");
;   __syncthreads();
;   for (int kt = 0; kt < nk; kt += 2) {
;     if (kt + 1 < nk) G_GLDS(kt + 1, 1);
	v_lshlrev_b64 v[0:1], 11, v[0:1]
	v_lshlrev_b32_e32 v157, 4, v6
	v_lshl_add_u64 v[104:105], s[70:71], 0, v[0:1]
	v_mov_b32_e32 v0, 0
	v_lshl_add_u32 v155, v5, 7, 0
	s_mov_b32 s15, 0
	v_mov_b32_e32 v1, v0
	v_mov_b32_e32 v2, v0
	v_mov_b32_e32 v3, v0
	v_mov_b32_e32 v4, v0
	v_mov_b32_e32 v5, v0
	v_mov_b32_e32 v6, v0
	v_mov_b32_e32 v7, v0
	v_mov_b32_e32 v8, v0
	v_mov_b32_e32 v9, v0
	v_mov_b32_e32 v10, v0
	v_mov_b32_e32 v11, v0
	v_mov_b32_e32 v12, v0
	v_mov_b32_e32 v13, v0
	v_mov_b32_e32 v14, v0
	v_mov_b32_e32 v15, v0
	v_mov_b32_e32 v16, v0
	v_mov_b32_e32 v17, v0
	v_mov_b32_e32 v18, v0
	v_mov_b32_e32 v19, v0
	v_mov_b32_e32 v20, v0
	v_mov_b32_e32 v21, v0
	v_mov_b32_e32 v22, v0
	v_mov_b32_e32 v23, v0
	v_mov_b32_e32 v24, v0
	v_mov_b32_e32 v25, v0
	v_mov_b32_e32 v26, v0
	v_mov_b32_e32 v27, v0
	v_mov_b32_e32 v28, v0
	v_mov_b32_e32 v29, v0
	v_mov_b32_e32 v30, v0
	v_mov_b32_e32 v31, v0
	v_mov_b32_e32 v32, v0
	v_mov_b32_e32 v33, v0
	v_mov_b32_e32 v34, v0
	v_mov_b32_e32 v35, v0
	v_mov_b32_e32 v36, v0
	v_mov_b32_e32 v37, v0
	v_mov_b32_e32 v38, v0
	v_mov_b32_e32 v39, v0
	v_mov_b32_e32 v40, v0
	v_mov_b32_e32 v41, v0
	v_mov_b32_e32 v42, v0
	v_mov_b32_e32 v43, v0
	v_mov_b32_e32 v44, v0
	v_mov_b32_e32 v45, v0
	v_mov_b32_e32 v46, v0
	v_mov_b32_e32 v47, v0
	v_mov_b32_e32 v48, v0
	s_waitcnt vmcnt(0)
	v_mov_b32_e32 v49, v0
	v_mov_b32_e32 v50, v0
	v_mov_b32_e32 v51, v0
	v_mov_b32_e32 v52, v0
	v_mov_b32_e32 v53, v0
	v_mov_b32_e32 v54, v0
	v_mov_b32_e32 v55, v0
	v_mov_b32_e32 v56, v0
	v_mov_b32_e32 v57, v0
	v_mov_b32_e32 v58, v0
	v_mov_b32_e32 v59, v0
	v_mov_b32_e32 v60, v0
	v_mov_b32_e32 v61, v0
	v_mov_b32_e32 v62, v0
	v_mov_b32_e32 v63, v0
	v_mov_b32_e32 v64, v0
	v_mov_b32_e32 v65, v0
	v_mov_b32_e32 v66, v0
	v_mov_b32_e32 v67, v0
	v_mov_b32_e32 v68, v0
	v_mov_b32_e32 v69, v0
	v_mov_b32_e32 v70, v0
	v_mov_b32_e32 v71, v0
	v_mov_b32_e32 v72, v0
	v_mov_b32_e32 v73, v0
	v_mov_b32_e32 v74, v0
	v_mov_b32_e32 v75, v0
	v_mov_b32_e32 v76, v0
	v_mov_b32_e32 v77, v0
	v_mov_b32_e32 v78, v0
	v_mov_b32_e32 v79, v0
	v_mov_b32_e32 v80, v0
	v_mov_b32_e32 v81, v0
	v_mov_b32_e32 v82, v0
	v_mov_b32_e32 v83, v0
	v_mov_b32_e32 v84, v0
	v_mov_b32_e32 v85, v0
	v_mov_b32_e32 v86, v0
	v_mov_b32_e32 v87, v0
	v_mov_b32_e32 v88, v0
	v_mov_b32_e32 v89, v0
	v_mov_b32_e32 v90, v0
	v_mov_b32_e32 v91, v0
	v_mov_b32_e32 v92, v0
	v_mov_b32_e32 v93, v0
	v_mov_b32_e32 v94, v0
	v_mov_b32_e32 v95, v0
	v_xor_b32_e32 v159, 32, v157
	v_xor_b32_e32 v160, 64, v157
	v_xor_b32_e32 v161, 0x60, v157
	s_mov_b64 s[18:19], 0x80
	s_mov_b64 s[42:43], 0x10080
	v_add_u32_e32 v162, v155, v157
	v_add_u32_e32 v163, v155, v159
	v_add_u32_e32 v164, v155, v160
	v_add_u32_e32 v165, v155, v161
	v_add_u32_e32 v166, v156, v157
	v_add_u32_e32 v167, v156, v159
	v_add_u32_e32 v168, v156, v160
	v_add_u32_e32 v169, v156, v161
	v_add_u32_e32 v170, v158, v157
	v_add_u32_e32 v171, v158, v159
	v_add_u32_e32 v172, v158, v160
	v_add_u32_e32 v173, v158, v161
	v_lshl_add_u64 v[174:175], v[104:105], 0, v[100:101]
	v_lshl_add_u64 v[176:177], v[102:103], 0, v[100:101]
	v_readfirstlane_b32 s100, v124
	s_add_u32 m0, s100, 0x6000
	v_lshl_add_u64 v[106:107], v[174:175], 0, s[96:97]
	global_load_lds_dwordx4 v[106:107], off
	s_add_u32 m0, s100, 0x7000
	v_lshl_add_u64 v[106:107], v[174:175], 0, s[50:51]
	global_load_lds_dwordx4 v[106:107], off
	s_add_u32 m0, s100, 0x8000
	v_lshl_add_u64 v[106:107], v[174:175], 0, s[24:25]
	global_load_lds_dwordx4 v[106:107], off
	s_add_u32 m0, s100, 0x9000
	v_lshl_add_u64 v[106:107], v[174:175], 0, s[26:27]
	global_load_lds_dwordx4 v[106:107], off
	s_waitcnt vmcnt(4) lgkmcnt(0)
	s_barrier
	ds_read_b128 v[236:239], v166 offset:49152
	ds_read_b128 v[240:243], v166 offset:53248
	ds_read_b128 v[224:227], v162
	ds_read_b128 v[228:231], v162 offset:4096
	s_mov_b32 s15, 0

; template <int EPI, int MI>
; DI void gemm_tile(const GemmDesc& g, int tm, int tn, char* smem) {
;     ...
;   const int tid = get_tid(), lane = tid & 63, wave = tid >> 6, r = lane & 31, hh = lane >> 5;
;   const int wm = wave >> 1, wn = wave & 1;
;   const int m0 = tm * BM, n0 = tn * 128;
;   const int nk = g.K >> 6;
;   f32x16 acc[MI][2];
; #pragma unroll
;   for (int a = 0; a < MI; ++a)
; #pragma unroll
;     for (int b = 0; b < 2; ++b)
; #pragma unroll
;       for (int i = 0; i < 16; ++i) acc[a][b][i] = 0.f;
;   const int srow = tid >> 3;
;   const int schunk = (tid & 7) ^ ((srow & 7) ^ ((srow >> 3) & 3));
;     ...
;   const int rowA = wm * (32 * MI) + r, rowB = wn * 64 + r;
;   const int hk = hh ^ ((r & 7) ^ ((r >> 3) & 3));
;     ...
;   G_GLDS(0, 0);
;   asm volatile("s_waitcnt vmcnt(0)" ::: "memory");
;   __syncthreads();
; template <int EPI, int MI>
; DI void gemm_phase(const GemmDesc& g, char* smem, int vb, int nvb) {
;     ...
;   for (int q = start; q < local; q += step) {
;     const int mg = q / per;
;     const int rem = q - mg * per;
;     const int tn = rem / PM;
;     const int tm = mbase + mg * PM + (rem - tn * PM);
.LBB0_254:
	s_abs_i32 s0, s42
	v_readlane_b32 s1, v219, 48
	s_mul_hi_u32 s1, s0, s1
	v_readlane_b32 s17, v219, 47
	s_mul_i32 s4, s1, s17
	s_sub_i32 s0, s0, s4
	s_ashr_i32 s15, s42, 31
	s_add_i32 s4, s1, 1
	s_sub_i32 s5, s0, s17
	s_cmp_ge_u32 s0, s17
	s_cselect_b32 s1, s4, s1
	s_cselect_b32 s0, s5, s0
	s_add_i32 s4, s1, 1
	s_cmp_ge_u32 s0, s17
	s_cselect_b32 s0, s4, s1
	s_xor_b32 s16, s0, s15
	s_sub_i32 s0, s16, s15
	s_mul_i32 s1, s0, s17
	s_sub_i32 s1, s42, s1
	s_abs_i32 s4, s1
	v_readlane_b32 s5, v219, 46
	s_mul_hi_u32 s5, s4, s5
	v_readlane_b32 s43, v218, 32
	s_mul_i32 s18, s5, s43
	s_sub_i32 s4, s4, s18
	s_ashr_i32 s17, s1, 31
	s_add_i32 s18, s5, 1
	s_sub_i32 s19, s4, s43
	s_cmp_ge_u32 s4, s43
	s_cselect_b32 s5, s18, s5
	s_cselect_b32 s4, s19, s4
	s_add_i32 s18, s5, 1
	s_cmp_ge_u32 s4, s43
	s_cselect_b32 s4, s18, s5
	s_xor_b32 s18, s4, s17
	v_mov_b32_e32 v97, v132
	s_sub_i32 s4, s18, s17
	s_mul_i32 s0, s0, s43
	v_ashrrev_i32_e32 v6, 3, v97
	s_mul_i32 s5, s4, s43
	s_waitcnt vmcnt(8)
	v_ashrrev_i32_e32 v109, 7, v97
	v_bfe_u32 v1, v97, 6, 2
	v_xor_b32_e32 v2, v6, v97
	s_add_i32 s0, s0, s54
	s_sub_i32 s1, s1, s5
	v_and_b32_e32 v108, 31, v97
	v_bitop3_b32 v2, v2, v1, 7 bitop3:0x6c
	v_mul_lo_u32 v1, v109, s6
	s_add_i32 s1, s0, s1
	s_lshl_b32 s0, s4, 7
	v_and_b32_e32 v0, 7, v97
	v_or_b32_e32 v7, v1, v108
	v_lshrrev_b32_e32 v1, 3, v97
	v_readlane_b32 s4, v221, 5
	s_mul_i32 s43, s1, 0xc0
	v_bfe_u32 v115, v97, 5, 1
	v_bitop3_b32 v0, v1, v0, 3 bitop3:0x6c
	v_readlane_b32 s5, v221, 6
	v_xor_b32_e32 v8, v0, v115
	v_add_u32_e32 v3, s43, v6
	v_mov_b64_e32 v[0:1], s[4:5]
	s_movk_i32 s19, 0x1600
	v_mad_i64_i32 v[0:1], s[4:5], v3, s19, v[0:1]
	v_readlane_b32 s4, v221, 10
	v_readlane_b32 s5, v221, 11
	v_lshlrev_b32_e32 v98, 4, v2
	v_add_u32_e32 v9, s0, v6
	v_mov_b64_e32 v[2:3], s[4:5]
	v_lshlrev_b32_e32 v120, 4, v97
	v_mad_i64_i32 v[2:3], s[4:5], v9, s19, v[2:3]
	v_add_u32_e32 v121, 0, v120
	v_mov_b32_e32 v99, v96
	v_readfirstlane_b32 s4, v121
	v_add_u32_e32 v122, 0x1000, v121
	v_lshl_add_u64 v[0:1], v[0:1], 0, v[98:99]
	s_mov_b32 m0, s4
	s_mov_b64 s[44:45], 0x2c000
	v_readfirstlane_b32 s4, v122
	v_add_u32_e32 v123, 0x2000, v121
	global_load_lds_dwordx4 v[0:1], off
	v_lshl_add_u64 v[4:5], v[0:1], 0, s[44:45]
	s_mov_b32 m0, s4
	s_mov_b64 s[46:47], 0x58000
	v_readfirstlane_b32 s4, v123
	v_add_u32_e32 v124, 0x3000, v121
	global_load_lds_dwordx4 v[4:5], off
	v_lshl_add_u64 v[4:5], v[0:1], 0, s[46:47]
	s_mov_b32 m0, s4
	s_mov_b64 s[52:53], 0x84000
	v_readfirstlane_b32 s4, v124
	global_load_lds_dwordx4 v[4:5], off
	v_lshl_add_u64 v[4:5], v[0:1], 0, s[52:53]
	s_mov_b32 m0, s4
	s_mov_b64 s[4:5], 0xb0000
	v_add_u32_e32 v125, 0x4000, v121
	global_load_lds_dwordx4 v[4:5], off
	v_lshl_add_u64 v[4:5], v[0:1], 0, s[4:5]
	v_readfirstlane_b32 s4, v125
	s_mov_b32 m0, s4
	s_mov_b64 s[4:5], 0xdc000
	v_add_u32_e32 v126, 0x5000, v121
	v_lshl_add_u64 v[0:1], v[0:1], 0, s[4:5]
	v_readfirstlane_b32 s4, v126
	v_add_u32_e32 v127, 0xc000, v121
	global_load_lds_dwordx4 v[4:5], off
	s_mov_b32 m0, s4
	v_readfirstlane_b32 s4, v127
	v_add_u32_e32 v128, 0xd000, v121
	global_load_lds_dwordx4 v[0:1], off
	v_lshl_add_u64 v[0:1], v[2:3], 0, v[98:99]
	s_mov_b32 m0, s4
	v_readfirstlane_b32 s4, v128
	v_add_u32_e32 v129, 0xe000, v121
	global_load_lds_dwordx4 v[0:1], off
	v_lshl_add_u64 v[2:3], v[0:1], 0, s[44:45]
	s_mov_b32 m0, s4
	v_readfirstlane_b32 s4, v129
	v_add_u32_e32 v130, 0xf000, v121
	global_load_lds_dwordx4 v[2:3], off
	v_lshl_add_u64 v[2:3], v[0:1], 0, s[46:47]
	s_mov_b32 m0, s4
	v_readfirstlane_b32 s4, v130
	global_load_lds_dwordx4 v[2:3], off
	v_lshl_add_u64 v[0:1], v[0:1], 0, s[52:53]
	s_mov_b32 m0, s4
	s_mul_i32 s15, s15, 7
	global_load_lds_dwordx4 v[0:1], off
	s_add_i32 s17, s17, s15
	s_sub_i32 s4, s17, s18
	s_mul_i32 s16, s16, 7
	s_sub_i32 s4, s4, s16
	v_readlane_b32 s5, v218, 33
	v_lshlrev_b32_e32 v0, 7, v97
	s_mul_i32 s4, s5, s4
	v_and_b32_e32 v0, 0x2f80, v0
	s_add_i32 s4, s4, s39
	s_waitcnt vmcnt(0)
; template <int EPI, int MI>
; DI void gemm_tile(const GemmDesc& g, int tm, int tn, char* smem) {
;     ...
;   f32x16 acc[MI][2];
; #pragma unroll
;   for (int a = 0; a < MI; ++a)
; #pragma unroll
;     for (int b = 0; b < 2; ++b)
; #pragma unroll
;       for (int i = 0; i < 16; ++i) acc[a][b][i] = 0.f;
;   const int srow = tid >> 3;
;   const int schunk = (tid & 7) ^ ((srow & 7) ^ ((srow >> 3) & 3));
;     ...
;   const int rowA = wm * (32 * MI) + r, rowB = wn * 64 + r;
;   const int hk = hh ^ ((r & 7) ^ ((r >> 3) & 3));
;     ...
;   G_GLDS(0, 0);
;   asm volatile("s_waitcnt vmcnt(0)" ::: "memory");
;   __syncthreads();
;   for (int kt = 0; kt < nk; kt += 2) {
;     if (kt + 1 < nk) G_GLDS(kt + 1, 1);
	v_add_u32_e32 v153, 0, v0
	v_add_u32_e32 v155, s10, v0
	v_add_u32_e32 v2, s4, v6
	v_mov_b64_e32 v[0:1], s[70:71]
	v_lshlrev_b32_e32 v154, 4, v8
	v_mad_i64_i32 v[100:101], s[4:5], v2, s19, v[0:1]
	v_mad_i64_i32 v[102:103], s[4:5], v9, s19, v[0:1]
	v_mov_b32_e32 v0, 0
	v_lshl_add_u32 v131, v7, 7, 0
	v_xor_b32_e32 v156, 32, v154
	v_xor_b32_e32 v157, 64, v154
	v_xor_b32_e32 v158, 0x60, v154
	s_mov_b32 s15, 0
	v_mov_b32_e32 v1, v0
	v_mov_b32_e32 v2, v0
	v_mov_b32_e32 v3, v0
	v_mov_b32_e32 v4, v0
	v_mov_b32_e32 v5, v0
	v_mov_b32_e32 v6, v0
	v_mov_b32_e32 v7, v0
	v_mov_b32_e32 v8, v0
	v_mov_b32_e32 v9, v0
	v_mov_b32_e32 v10, v0
	v_mov_b32_e32 v11, v0
	v_mov_b32_e32 v12, v0
	v_mov_b32_e32 v13, v0
	v_mov_b32_e32 v14, v0
	v_mov_b32_e32 v15, v0
	v_mov_b32_e32 v16, v0
	v_mov_b32_e32 v17, v0
	v_mov_b32_e32 v18, v0
	v_mov_b32_e32 v19, v0
	v_mov_b32_e32 v20, v0
	v_mov_b32_e32 v21, v0
	v_mov_b32_e32 v22, v0
	v_mov_b32_e32 v23, v0
	v_mov_b32_e32 v24, v0
	v_mov_b32_e32 v25, v0
	v_mov_b32_e32 v26, v0
	v_mov_b32_e32 v27, v0
	v_mov_b32_e32 v28, v0
	v_mov_b32_e32 v29, v0
	v_mov_b32_e32 v30, v0
	v_mov_b32_e32 v31, v0
	v_mov_b32_e32 v32, v0
	v_mov_b32_e32 v33, v0
	v_mov_b32_e32 v34, v0
	v_mov_b32_e32 v35, v0
	v_mov_b32_e32 v36, v0
	v_mov_b32_e32 v37, v0
	v_mov_b32_e32 v38, v0
	v_mov_b32_e32 v39, v0
	v_mov_b32_e32 v40, v0
	v_mov_b32_e32 v41, v0
	v_mov_b32_e32 v42, v0
	v_mov_b32_e32 v43, v0
	v_mov_b32_e32 v44, v0
	v_mov_b32_e32 v45, v0
	v_mov_b32_e32 v46, v0
	v_mov_b32_e32 v47, v0
	v_mov_b32_e32 v48, v0
	s_waitcnt vmcnt(0)
	v_mov_b32_e32 v49, v0
	v_mov_b32_e32 v50, v0
	v_mov_b32_e32 v51, v0
	v_mov_b32_e32 v52, v0
	v_mov_b32_e32 v53, v0
	v_mov_b32_e32 v54, v0
	v_mov_b32_e32 v55, v0
	v_mov_b32_e32 v56, v0
	v_mov_b32_e32 v57, v0
	v_mov_b32_e32 v58, v0
	v_mov_b32_e32 v59, v0
	v_mov_b32_e32 v60, v0
	v_mov_b32_e32 v61, v0
	v_mov_b32_e32 v62, v0
	v_mov_b32_e32 v63, v0
	v_mov_b32_e32 v64, v0
	v_mov_b32_e32 v65, v0
	v_mov_b32_e32 v66, v0
	v_mov_b32_e32 v67, v0
	v_mov_b32_e32 v68, v0
	v_mov_b32_e32 v69, v0
	v_mov_b32_e32 v70, v0
	v_mov_b32_e32 v71, v0
	v_mov_b32_e32 v72, v0
	v_mov_b32_e32 v73, v0
	v_mov_b32_e32 v74, v0
	v_mov_b32_e32 v75, v0
	v_mov_b32_e32 v76, v0
	v_mov_b32_e32 v77, v0
	v_mov_b32_e32 v78, v0
	v_mov_b32_e32 v79, v0
	v_mov_b32_e32 v80, v0
	v_mov_b32_e32 v81, v0
	v_mov_b32_e32 v82, v0
	v_mov_b32_e32 v83, v0
	v_mov_b32_e32 v84, v0
	v_mov_b32_e32 v85, v0
	v_mov_b32_e32 v86, v0
	v_mov_b32_e32 v87, v0
	v_mov_b32_e32 v88, v0
	v_mov_b32_e32 v89, v0
	v_mov_b32_e32 v90, v0
	v_mov_b32_e32 v91, v0
	v_mov_b32_e32 v92, v0
	v_mov_b32_e32 v93, v0
	v_mov_b32_e32 v94, v0
	v_mov_b32_e32 v95, v0
	v_add_u32_e32 v162, v131, v154
	v_add_u32_e32 v163, v131, v156
	v_add_u32_e32 v164, v131, v157
	v_add_u32_e32 v165, v131, v158
	v_add_u32_e32 v166, v153, v154
	v_add_u32_e32 v167, v153, v156
	v_add_u32_e32 v168, v153, v157
	v_add_u32_e32 v169, v153, v158
	v_add_u32_e32 v170, v155, v154
	v_add_u32_e32 v171, v155, v156
	v_add_u32_e32 v172, v155, v157
	v_add_u32_e32 v173, v155, v158
	v_lshl_add_u64 v[252:253], v[100:101], 0, v[98:99]
	v_lshl_add_u64 v[254:255], v[102:103], 0, v[98:99]
	v_readfirstlane_b32 s100, v121
	s_mov_b64 s[4:5], 0x80
	s_mov_b64 s[16:17], 0x5872080
	s_add_u32 m0, s100, 0x6000
	v_lshl_add_u64 v[106:107], v[252:253], 0, s[16:17]
	global_load_lds_dwordx4 v[106:107], off
	s_mov_b64 s[16:17], 0x589e080
	s_add_u32 m0, s100, 0x7000
	v_lshl_add_u64 v[106:107], v[252:253], 0, s[16:17]
	global_load_lds_dwordx4 v[106:107], off
	s_mov_b64 s[16:17], 0x58ca080
	s_add_u32 m0, s100, 0x8000
	v_lshl_add_u64 v[106:107], v[252:253], 0, s[16:17]
	global_load_lds_dwordx4 v[106:107], off
	s_mov_b64 s[16:17], 0x58f6080
	s_add_u32 m0, s100, 0x9000
	v_lshl_add_u64 v[106:107], v[252:253], 0, s[16:17]
	global_load_lds_dwordx4 v[106:107], off
	s_mov_b64 s[16:17], 0x5922080
	s_add_u32 m0, s100, 0xa000
	v_lshl_add_u64 v[106:107], v[252:253], 0, s[16:17]
	global_load_lds_dwordx4 v[106:107], off
	s_mov_b64 s[16:17], 0x594e080
	s_add_u32 m0, s100, 0xb000
	v_lshl_add_u64 v[106:107], v[252:253], 0, s[16:17]
	global_load_lds_dwordx4 v[106:107], off
	v_lshl_add_u64 v[252:253], v[252:253], 0, s[4:5]
	s_mov_b64 s[16:17], 0x1600080
	s_add_u32 m0, s100, 0x10000
	v_lshl_add_u64 v[106:107], v[254:255], 0, s[16:17]
	global_load_lds_dwordx4 v[106:107], off
	s_mov_b64 s[16:17], 0x162c080
	s_add_u32 m0, s100, 0x11000
	v_lshl_add_u64 v[106:107], v[254:255], 0, s[16:17]
	global_load_lds_dwordx4 v[106:107], off
	s_mov_b64 s[16:17], 0x1658080
	s_add_u32 m0, s100, 0x12000
	v_lshl_add_u64 v[106:107], v[254:255], 0, s[16:17]
	global_load_lds_dwordx4 v[106:107], off
	s_mov_b64 s[16:17], 0x1684080
	s_add_u32 m0, s100, 0x13000
	v_lshl_add_u64 v[106:107], v[254:255], 0, s[16:17]
	global_load_lds_dwordx4 v[106:107], off
	v_lshl_add_u64 v[254:255], v[254:255], 0, s[4:5]
	s_waitcnt vmcnt(10) lgkmcnt(0)
	s_barrier
	ds_read_b128 v[236:239], v166 offset:49152
	ds_read_b128 v[240:243], v166 offset:53248
	ds_read_b128 v[224:227], v162
	ds_read_b128 v[228:231], v162 offset:4096
	s_mov_b32 s15, 0

; template <int EPI, int MI>
; DI void gemm_tile(const GemmDesc& g, int tm, int tn, char* smem) {
;     ...
;   const int tid = get_tid(), lane = tid & 63, wave = tid >> 6, r = lane & 31, hh = lane >> 5;
;   const int wm = wave >> 1, wn = wave & 1;
;   const int m0 = tm * BM, n0 = tn * 128;
;   const int nk = g.K >> 6;
;   f32x16 acc[MI][2];
; #pragma unroll
;   for (int a = 0; a < MI; ++a)
; #pragma unroll
;     for (int b = 0; b < 2; ++b)
; #pragma unroll
;       for (int i = 0; i < 16; ++i) acc[a][b][i] = 0.f;
;   const int srow = tid >> 3;
;   const int schunk = (tid & 7) ^ ((srow & 7) ^ ((srow >> 3) & 3));
;     ...
;   const int rowA = wm * (32 * MI) + r, rowB = wn * 64 + r;
;   const int hk = hh ^ ((r & 7) ^ ((r >> 3) & 3));
;     ...
;   G_GLDS(0, 0);
;   asm volatile("s_waitcnt vmcnt(0)" ::: "memory");
;   __syncthreads();
; template <int EPI, int MI>
; DI void gemm_phase(const GemmDesc& g, char* smem, int vb, int nvb) {
;     ...
;   for (int q = start; q < local; q += step) {
;     const int mg = q / per;
;     const int rem = q - mg * per;
;     const int tn = rem / PM;
;     const int tm = mbase + mg * PM + (rem - tn * PM);
.LBB0_371:
	s_abs_i32 s1, s47
	s_mul_hi_u32 s4, s1, s45
	s_mul_i32 s5, s4, s43
	s_sub_i32 s1, s1, s5
	s_ashr_i32 s0, s47, 31
	s_add_i32 s5, s4, 1
	s_sub_i32 s15, s1, s43
	s_cmp_ge_u32 s1, s43
	s_cselect_b32 s4, s5, s4
	s_cselect_b32 s1, s15, s1
	s_add_i32 s5, s4, 1
	s_cmp_ge_u32 s1, s43
	s_cselect_b32 s1, s5, s4
	s_xor_b32 s1, s1, s0
	s_sub_i32 s4, s1, s0
	s_mul_i32 s5, s4, s43
	s_sub_i32 s5, s47, s5
	s_abs_i32 s16, s5
	v_readlane_b32 s17, v219, 46
	s_mul_hi_u32 s17, s16, s17
	v_readlane_b32 s38, v218, 32
	s_mul_i32 s18, s17, s38
	s_sub_i32 s16, s16, s18
	s_ashr_i32 s15, s5, 31
	s_add_i32 s18, s17, 1
	s_sub_i32 s19, s16, s38
	s_cmp_ge_u32 s16, s38
	s_cselect_b32 s17, s18, s17
	s_cselect_b32 s16, s19, s16
	s_add_i32 s18, s17, 1
	s_cmp_ge_u32 s16, s38
	s_cselect_b32 s16, s18, s17
	s_xor_b32 s16, s16, s15
	s_sub_i32 s17, s16, s15
	s_sub_i32 s18, s4, s17
	v_mov_b32_e32 v97, v132
	s_mul_i32 s18, s18, s38
	s_add_i32 s5, s5, s54
	s_add_i32 s48, s5, s18
	v_ashrrev_i32_e32 v0, 7, v97
	v_and_b32_e32 v1, 7, v97
	v_mul_lo_u32 v115, v0, s6
	v_lshrrev_b32_e32 v0, 3, v97
	s_mulk_i32 s48, 0xc0
	s_waitcnt vmcnt(8)
	v_bfe_u32 v109, v97, 5, 1
	v_ashrrev_i32_e32 v8, 3, v97
	v_bitop3_b32 v0, v0, v1, 3 bitop3:0x6c
	v_bfe_u32 v2, v97, 6, 2
	v_xor_b32_e32 v3, v8, v97
	v_xor_b32_e32 v10, v0, v109
	v_add_u32_e32 v0, s48, v8
	s_lshl_b32 s49, s17, 7
	v_bitop3_b32 v2, v3, v2, 7 bitop3:0x6c
	v_ashrrev_i32_e32 v1, 31, v0
	v_readlane_b32 s18, v223, 59
	v_lshlrev_b64 v[0:1], 11, v[0:1]
	v_readlane_b32 s19, v223, 60
	v_lshlrev_b32_e32 v98, 4, v2
	v_add_u32_e32 v2, s49, v8
	v_lshlrev_b32_e32 v120, 4, v97
	v_lshl_add_u64 v[0:1], s[18:19], 0, v[0:1]
	v_ashrrev_i32_e32 v3, 31, v2
	v_readlane_b32 s18, v221, 16
	v_add_u32_e32 v121, 0, v120
	v_mov_b32_e32 v99, v96
	v_lshlrev_b64 v[2:3], 11, v[2:3]
	v_readlane_b32 s19, v221, 17
	v_readfirstlane_b32 s5, v121
	v_add_u32_e32 v122, 0x1000, v121
	v_lshl_add_u64 v[0:1], v[0:1], 0, v[98:99]
	v_lshl_add_u64 v[4:5], s[18:19], 0, v[2:3]
	s_mov_b32 m0, s5
	s_mov_b64 s[18:19], 0x10000
	v_readfirstlane_b32 s5, v122
	v_add_u32_e32 v123, 0x2000, v121
	global_load_lds_dwordx4 v[0:1], off
	v_lshl_add_u64 v[6:7], v[0:1], 0, s[18:19]
	s_mov_b32 m0, s5
	s_mov_b64 s[38:39], 0x20000
	v_readfirstlane_b32 s5, v123
	v_add_u32_e32 v124, 0x3000, v121
	global_load_lds_dwordx4 v[6:7], off
	v_lshl_add_u64 v[6:7], v[0:1], 0, s[38:39]
	s_mov_b32 m0, s5
	s_mov_b64 s[52:53], 0x30000
	v_readfirstlane_b32 s5, v124
	v_add_u32_e32 v125, 0x4000, v121
	global_load_lds_dwordx4 v[6:7], off
	v_lshl_add_u64 v[6:7], v[0:1], 0, s[52:53]
	s_mov_b32 m0, s5
	s_mov_b64 s[72:73], 0x40000
	v_readfirstlane_b32 s5, v125
	v_add_u32_e32 v126, 0x5000, v121
	global_load_lds_dwordx4 v[6:7], off
	v_lshl_add_u64 v[6:7], v[0:1], 0, s[72:73]
	s_mov_b32 m0, s5
	s_mov_b64 s[72:73], 0x50000
	v_readfirstlane_b32 s5, v126
	v_add_u32_e32 v127, 0xc000, v121
	global_load_lds_dwordx4 v[6:7], off
	v_lshl_add_u64 v[0:1], v[0:1], 0, s[72:73]
	s_mov_b32 m0, s5
	v_readfirstlane_b32 s5, v127
	v_add_u32_e32 v128, 0xd000, v121
	global_load_lds_dwordx4 v[0:1], off
	v_lshl_add_u64 v[0:1], v[4:5], 0, v[98:99]
	s_mov_b32 m0, s5
	v_readfirstlane_b32 s5, v128
	v_add_u32_e32 v129, 0xe000, v121
	global_load_lds_dwordx4 v[0:1], off
	v_lshl_add_u64 v[4:5], v[0:1], 0, s[18:19]
	s_mov_b32 m0, s5
	v_readfirstlane_b32 s5, v129
	v_add_u32_e32 v130, 0xf000, v121
	global_load_lds_dwordx4 v[4:5], off
	v_lshl_add_u64 v[4:5], v[0:1], 0, s[38:39]
	s_mov_b32 m0, s5
	v_readfirstlane_b32 s5, v130
	global_load_lds_dwordx4 v[4:5], off
	v_lshl_add_u64 v[0:1], v[0:1], 0, s[52:53]
	s_mov_b32 m0, s5
	s_add_i32 s1, s1, s15
	global_load_lds_dwordx4 v[0:1], off
	s_mul_i32 s4, s20, s4
	s_sub_i32 s1, s1, s4
	s_sub_i32 s1, s1, s16
	s_sub_i32 s0, s1, s0
	v_readlane_b32 s1, v218, 33
	v_lshlrev_b32_e32 v0, 7, v97
	s_mul_i32 s0, s1, s0
	v_and_b32_e32 v0, 0x2f80, v0
	s_add_i32 s0, s0, s46
	v_add_u32_e32 v153, 0, v0
	v_add_u32_e32 v155, s10, v0
	v_add_u32_e32 v0, s0, v8
	v_ashrrev_i32_e32 v1, 31, v0
	v_and_b32_e32 v108, 31, v97
	s_waitcnt vmcnt(0)
; template <int EPI, int MI>
; DI void gemm_tile(const GemmDesc& g, int tm, int tn, char* smem) {
;     ...
;   f32x16 acc[MI][2];
; #pragma unroll
;   for (int a = 0; a < MI; ++a)
; #pragma unroll
;     for (int b = 0; b < 2; ++b)
; #pragma unroll
;       for (int i = 0; i < 16; ++i) acc[a][b][i] = 0.f;
;   const int srow = tid >> 3;
;   const int schunk = (tid & 7) ^ ((srow & 7) ^ ((srow >> 3) & 3));
;     ...
;   const int rowA = wm * (32 * MI) + r, rowB = wn * 64 + r;
;   const int hk = hh ^ ((r & 7) ^ ((r >> 3) & 3));
;     ...
;   G_GLDS(0, 0);
;   asm volatile("s_waitcnt vmcnt(0)" ::: "memory");
;   __syncthreads();
;   for (int kt = 0; kt < nk; kt += 2) {
;     if (kt + 1 < nk) G_GLDS(kt + 1, 1);
	v_lshlrev_b64 v[0:1], 11, v[0:1]
	v_or_b32_e32 v9, v115, v108
	v_lshlrev_b32_e32 v154, 4, v10
	v_lshl_add_u64 v[102:103], s[70:71], 0, v[0:1]
	v_mov_b32_e32 v0, 0
	v_lshl_add_u32 v131, v9, 7, 0
	v_xor_b32_e32 v156, 32, v154
	v_xor_b32_e32 v157, 64, v154
	v_xor_b32_e32 v158, 0x60, v154
	v_lshl_add_u64 v[100:101], s[70:71], 0, v[2:3]
	s_mov_b32 s4, 0
	v_mov_b32_e32 v1, v0
	v_mov_b32_e32 v2, v0
	v_mov_b32_e32 v3, v0
	v_mov_b32_e32 v4, v0
	v_mov_b32_e32 v5, v0
	v_mov_b32_e32 v6, v0
	v_mov_b32_e32 v7, v0
	v_mov_b32_e32 v8, v0
	v_mov_b32_e32 v9, v0
	v_mov_b32_e32 v10, v0
	v_mov_b32_e32 v11, v0
	v_mov_b32_e32 v12, v0
	v_mov_b32_e32 v13, v0
	v_mov_b32_e32 v14, v0
	v_mov_b32_e32 v15, v0
	v_mov_b32_e32 v16, v0
	v_mov_b32_e32 v17, v0
	v_mov_b32_e32 v18, v0
	v_mov_b32_e32 v19, v0
	v_mov_b32_e32 v20, v0
	v_mov_b32_e32 v21, v0
	v_mov_b32_e32 v22, v0
	v_mov_b32_e32 v23, v0
	v_mov_b32_e32 v24, v0
	v_mov_b32_e32 v25, v0
	v_mov_b32_e32 v26, v0
	v_mov_b32_e32 v27, v0
	v_mov_b32_e32 v28, v0
	v_mov_b32_e32 v29, v0
	v_mov_b32_e32 v30, v0
	v_mov_b32_e32 v31, v0
	v_mov_b32_e32 v32, v0
	v_mov_b32_e32 v33, v0
	v_mov_b32_e32 v34, v0
	v_mov_b32_e32 v35, v0
	v_mov_b32_e32 v36, v0
	v_mov_b32_e32 v37, v0
	v_mov_b32_e32 v38, v0
	v_mov_b32_e32 v39, v0
	v_mov_b32_e32 v40, v0
	v_mov_b32_e32 v41, v0
	v_mov_b32_e32 v42, v0
	v_mov_b32_e32 v43, v0
	v_mov_b32_e32 v44, v0
	v_mov_b32_e32 v45, v0
	v_mov_b32_e32 v46, v0
	v_mov_b32_e32 v47, v0
	v_mov_b32_e32 v48, v0
	s_waitcnt vmcnt(0)
	v_mov_b32_e32 v49, v0
	v_mov_b32_e32 v50, v0
	v_mov_b32_e32 v51, v0
	v_mov_b32_e32 v52, v0
	v_mov_b32_e32 v53, v0
	v_mov_b32_e32 v54, v0
	v_mov_b32_e32 v55, v0
	v_mov_b32_e32 v56, v0
	v_mov_b32_e32 v57, v0
	v_mov_b32_e32 v58, v0
	v_mov_b32_e32 v59, v0
	v_mov_b32_e32 v60, v0
	v_mov_b32_e32 v61, v0
	v_mov_b32_e32 v62, v0
	v_mov_b32_e32 v63, v0
	v_mov_b32_e32 v64, v0
	v_mov_b32_e32 v65, v0
	v_mov_b32_e32 v66, v0
	v_mov_b32_e32 v67, v0
	v_mov_b32_e32 v68, v0
	v_mov_b32_e32 v69, v0
	v_mov_b32_e32 v70, v0
	v_mov_b32_e32 v71, v0
	v_mov_b32_e32 v72, v0
	v_mov_b32_e32 v73, v0
	v_mov_b32_e32 v74, v0
	v_mov_b32_e32 v75, v0
	v_mov_b32_e32 v76, v0
	v_mov_b32_e32 v77, v0
	v_mov_b32_e32 v78, v0
	v_mov_b32_e32 v79, v0
	v_mov_b32_e32 v80, v0
	v_mov_b32_e32 v81, v0
	v_mov_b32_e32 v82, v0
	v_mov_b32_e32 v83, v0
	v_mov_b32_e32 v84, v0
	v_mov_b32_e32 v85, v0
	v_mov_b32_e32 v86, v0
	v_mov_b32_e32 v87, v0
	v_mov_b32_e32 v88, v0
	v_mov_b32_e32 v89, v0
	v_mov_b32_e32 v90, v0
	v_mov_b32_e32 v91, v0
	v_mov_b32_e32 v92, v0
	v_mov_b32_e32 v93, v0
	v_mov_b32_e32 v94, v0
	v_mov_b32_e32 v95, v0
	v_add_u32_e32 v162, v131, v154
	v_add_u32_e32 v163, v131, v156
	v_add_u32_e32 v164, v131, v157
	v_add_u32_e32 v165, v131, v158
	v_add_u32_e32 v166, v153, v154
	v_add_u32_e32 v167, v153, v156
	v_add_u32_e32 v168, v153, v157
	v_add_u32_e32 v169, v153, v158
	v_add_u32_e32 v170, v155, v154
	v_add_u32_e32 v171, v155, v156
	v_add_u32_e32 v172, v155, v157
	v_add_u32_e32 v173, v155, v158
	v_lshl_add_u64 v[252:253], v[102:103], 0, v[98:99]
	v_lshl_add_u64 v[254:255], v[100:101], 0, v[98:99]
	v_readfirstlane_b32 s100, v121
	s_mov_b64 s[0:1], 0x80
	s_add_u32 m0, s100, 0x6000
	v_lshl_add_u64 v[106:107], v[252:253], 0, s[96:97]
	global_load_lds_dwordx4 v[106:107], off
	s_add_u32 m0, s100, 0x7000
	v_lshl_add_u64 v[106:107], v[252:253], 0, s[50:51]
	global_load_lds_dwordx4 v[106:107], off
	s_add_u32 m0, s100, 0x8000
	v_lshl_add_u64 v[106:107], v[252:253], 0, s[24:25]
	global_load_lds_dwordx4 v[106:107], off
	s_add_u32 m0, s100, 0x9000
	v_lshl_add_u64 v[106:107], v[252:253], 0, s[26:27]
	global_load_lds_dwordx4 v[106:107], off
	s_waitcnt vmcnt(4) lgkmcnt(0)
	s_barrier
	ds_read_b128 v[236:239], v166 offset:49152
	ds_read_b128 v[240:243], v166 offset:53248
	ds_read_b128 v[224:227], v162
	ds_read_b128 v[228:231], v162 offset:4096
	s_mov_b32 s101, 0

; template <int EPI, int MI>
; DI void gemm_tile(const GemmDesc& g, int tm, int tn, char* smem) {
;     ...
;   const int tid = get_tid(), lane = tid & 63, wave = tid >> 6, r = lane & 31, hh = lane >> 5;
;   const int wm = wave >> 1, wn = wave & 1;
;   const int m0 = tm * BM, n0 = tn * 128;
;   const int nk = g.K >> 6;
;   f32x16 acc[MI][2];
; #pragma unroll
;   for (int a = 0; a < MI; ++a)
; #pragma unroll
;     for (int b = 0; b < 2; ++b)
; #pragma unroll
;       for (int i = 0; i < 16; ++i) acc[a][b][i] = 0.f;
;   const int srow = tid >> 3;
;   const int schunk = (tid & 7) ^ ((srow & 7) ^ ((srow >> 3) & 3));
;     ...
;   const int rowA = wm * (32 * MI) + r, rowB = wn * 64 + r;
;   const int hk = hh ^ ((r & 7) ^ ((r >> 3) & 3));
;     ...
;   G_GLDS(0, 0);
;   asm volatile("s_waitcnt vmcnt(0)" ::: "memory");
;   __syncthreads();
;   for (int kt = 0; kt < nk; kt += 2) {
;     if (kt + 1 < nk) G_GLDS(kt + 1, 1);
; template <int EPI, int MI>
; DI void gemm_phase(const GemmDesc& g, char* smem, int vb, int nvb) {
;     ...
;   for (int q = start; q < local; q += step) {
;     const int mg = q / per;
;     const int rem = q - mg * per;
;     const int tn = rem / PM;
;     const int tm = mbase + mg * PM + (rem - tn * PM);
.LBB0_1410:
	s_abs_i32 s1, s39
	s_mul_hi_u32 s40, s1, s17
	s_mul_i32 s41, s40, s15
	s_sub_i32 s1, s1, s41
	s_ashr_i32 s0, s39, 31
	s_add_i32 s41, s40, 1
	s_sub_i32 s42, s1, s15
	s_cmp_ge_u32 s1, s15
	s_cselect_b32 s40, s41, s40
	s_cselect_b32 s1, s42, s1
	s_add_i32 s41, s40, 1
	s_cmp_ge_u32 s1, s15
	s_cselect_b32 s1, s41, s40
	s_xor_b32 s1, s1, s0
	s_sub_i32 s40, s1, s0
	s_mul_i32 s41, s40, s15
	s_sub_i32 s42, s39, s41
	s_abs_i32 s41, s42
	s_mul_hi_u32 s44, s41, s18
	s_mul_i32 s45, s44, s4
	s_sub_i32 s41, s41, s45
	s_ashr_i32 s43, s42, 31
	s_add_i32 s45, s44, 1
	s_sub_i32 s46, s41, s4
	s_cmp_ge_u32 s41, s4
	s_cselect_b32 s44, s45, s44
	s_cselect_b32 s41, s46, s41
	s_add_i32 s45, s44, 1
	s_cmp_ge_u32 s41, s4
	s_cselect_b32 s41, s45, s44
	s_xor_b32 s44, s41, s43
	s_sub_i32 s41, s44, s43
	s_sub_i32 s40, s40, s41
	v_mov_b32_e32 v6, v132
	s_mul_i32 s40, s40, s4
	s_add_i32 s42, s42, s16
	s_add_i32 s42, s42, s40
	v_ashrrev_i32_e32 v76, 3, v6
	v_bfe_u32 v0, v6, 6, 2
	v_xor_b32_e32 v1, v76, v6
	s_lshl_b32 s40, s42, 7
	v_bitop3_b32 v2, v1, v0, 7 bitop3:0x6c
	v_ashrrev_i32_e32 v0, 1, v6
	v_and_b32_e32 v77, 7, v6
	v_and_b32_e32 v79, 0xffffffc0, v0
	v_lshrrev_b32_e32 v0, 3, v6
	v_add_u32_e32 v64, s40, v76
	v_bfe_u32 v78, v6, 5, 1
	v_bitop3_b32 v0, v0, v77, 3 bitop3:0x6c
	v_ashrrev_i32_e32 v65, 31, v64
	v_readlane_b32 s46, v223, 59
	v_and_b32_e32 v80, 31, v6
	v_bfe_u32 v81, v6, 6, 1
	v_xor_b32_e32 v9, v0, v78
	v_lshlrev_b64 v[0:1], 11, v[64:65]
	v_readlane_b32 s47, v223, 60
	v_lshlrev_b32_e32 v66, 4, v2
	v_lshl_add_u32 v2, s41, 7, v76
	v_lshlrev_b32_e32 v6, 4, v6
	v_lshl_add_u64 v[0:1], s[46:47], 0, v[0:1]
	v_ashrrev_i32_e32 v3, 31, v2
	v_readlane_b32 s46, v220, 54
	v_add_u32_e32 v65, 0, v6
	v_mov_b32_e32 v67, v96
	v_lshlrev_b64 v[2:3], 11, v[2:3]
	v_readlane_b32 s47, v220, 55
	v_readfirstlane_b32 s42, v65
	v_add_u32_e32 v82, 0x1000, v65
	v_lshl_add_u64 v[0:1], v[0:1], 0, v[66:67]
	v_lshl_add_u64 v[4:5], s[46:47], 0, v[2:3]
	s_mov_b32 m0, s42
	s_mov_b64 s[46:47], 0x10000
	v_readfirstlane_b32 s42, v82
	v_add_u32_e32 v83, 0x2000, v65
	global_load_lds_dwordx4 v[0:1], off
	v_lshl_add_u64 v[6:7], v[0:1], 0, s[46:47]
	s_mov_b32 m0, s42
	s_mov_b64 s[52:53], 0x20000
	v_readfirstlane_b32 s42, v83
	v_add_u32_e32 v84, 0x3000, v65
	global_load_lds_dwordx4 v[6:7], off
	v_lshl_add_u64 v[6:7], v[0:1], 0, s[52:53]
	s_mov_b32 m0, s42
	s_mov_b64 s[72:73], 0x30000
	v_readfirstlane_b32 s42, v84
	v_add_u32_e32 v85, 0x8000, v65
	global_load_lds_dwordx4 v[6:7], off
	v_lshl_add_u64 v[0:1], v[0:1], 0, s[72:73]
	s_mov_b32 m0, s42
	v_readfirstlane_b32 s42, v85
	v_add_u32_e32 v86, 0x9000, v65
	global_load_lds_dwordx4 v[0:1], off
	v_lshl_add_u64 v[0:1], v[4:5], 0, v[66:67]
	s_mov_b32 m0, s42
	v_readfirstlane_b32 s42, v86
	v_add_u32_e32 v87, 0xa000, v65
	global_load_lds_dwordx4 v[0:1], off
	v_lshl_add_u64 v[4:5], v[0:1], 0, s[46:47]
	s_mov_b32 m0, s42
	v_readfirstlane_b32 s42, v87
	v_add_u32_e32 v88, 0xb000, v65
	global_load_lds_dwordx4 v[4:5], off
	v_lshl_add_u64 v[4:5], v[0:1], 0, s[52:53]
	s_mov_b32 m0, s42
	v_readfirstlane_b32 s42, v88
	global_load_lds_dwordx4 v[4:5], off
	v_lshl_add_u64 v[0:1], v[0:1], 0, s[72:73]
	s_mov_b32 m0, s42
	s_mul_i32 s0, s0, 43
	global_load_lds_dwordx4 v[0:1], off
	s_add_i32 s43, s43, s0
	s_sub_i32 s0, s43, s44
	s_mul_i32 s1, s1, 43
	s_sub_i32 s0, s0, s1
	v_lshlrev_b32_e32 v0, 7, v80
	s_mul_i32 s0, s38, s0
	v_lshl_or_b32 v0, v81, 13, v0
	s_add_i32 s0, s0, s19
	v_add_u32_e32 v90, 0, v0
	v_add_u32_e32 v0, s0, v76
	v_ashrrev_i32_e32 v1, 31, v0
	s_waitcnt vmcnt(0)
	v_lshlrev_b64 v[0:1], 11, v[0:1]
	v_or_b32_e32 v8, v79, v80
	v_lshlrev_b32_e32 v91, 4, v9
	v_lshl_add_u64 v[68:69], s[70:71], 0, v[0:1]
	v_mov_b32_e32 v0, 0
	v_lshl_add_u32 v89, v8, 7, 0
	v_xor_b32_e32 v92, 32, v91
	v_xor_b32_e32 v93, 64, v91
	v_xor_b32_e32 v94, 0x60, v91
	v_lshl_add_u64 v[70:71], s[70:71], 0, v[2:3]
	s_mov_b32 s42, 0
	v_mov_b32_e32 v1, v0
	v_mov_b32_e32 v2, v0
	v_mov_b32_e32 v3, v0
	v_mov_b32_e32 v4, v0
	v_mov_b32_e32 v5, v0
	v_mov_b32_e32 v6, v0
	v_mov_b32_e32 v7, v0
	v_mov_b32_e32 v8, v0
	v_mov_b32_e32 v9, v0
	v_mov_b32_e32 v10, v0
	v_mov_b32_e32 v11, v0
	v_mov_b32_e32 v12, v0
	v_mov_b32_e32 v13, v0
	v_mov_b32_e32 v14, v0
	v_mov_b32_e32 v15, v0
	v_mov_b32_e32 v16, v0
	v_mov_b32_e32 v17, v0
	v_mov_b32_e32 v18, v0
	v_mov_b32_e32 v19, v0
	v_mov_b32_e32 v20, v0
	v_mov_b32_e32 v21, v0
	v_mov_b32_e32 v22, v0
	v_mov_b32_e32 v23, v0
	v_mov_b32_e32 v24, v0
	v_mov_b32_e32 v25, v0
	v_mov_b32_e32 v26, v0
	v_mov_b32_e32 v27, v0
	v_mov_b32_e32 v28, v0
	v_mov_b32_e32 v29, v0
	v_mov_b32_e32 v30, v0
	v_mov_b32_e32 v31, v0
	v_mov_b32_e32 v32, v0
	v_mov_b32_e32 v33, v0
	v_mov_b32_e32 v34, v0
	v_mov_b32_e32 v35, v0
	v_mov_b32_e32 v36, v0
	v_mov_b32_e32 v37, v0
	v_mov_b32_e32 v38, v0
	v_mov_b32_e32 v39, v0
	v_mov_b32_e32 v40, v0
	v_mov_b32_e32 v41, v0
	v_mov_b32_e32 v42, v0
	v_mov_b32_e32 v43, v0
	v_mov_b32_e32 v44, v0
	v_mov_b32_e32 v45, v0
	v_mov_b32_e32 v46, v0
	v_mov_b32_e32 v47, v0
	v_mov_b32_e32 v48, v0
	v_mov_b32_e32 v49, v0
	v_mov_b32_e32 v50, v0
	v_mov_b32_e32 v51, v0
	v_mov_b32_e32 v52, v0
	v_mov_b32_e32 v53, v0
	v_mov_b32_e32 v54, v0
	v_mov_b32_e32 v55, v0
	v_mov_b32_e32 v56, v0
	v_mov_b32_e32 v57, v0
	v_mov_b32_e32 v58, v0
	v_mov_b32_e32 v59, v0
	v_mov_b32_e32 v60, v0
	v_mov_b32_e32 v61, v0
	v_mov_b32_e32 v62, v0
	v_mov_b32_e32 v63, v0
	v_add_u32_e32 v98, v89, v91
	v_add_u32_e32 v99, v89, v92
	v_add_u32_e32 v100, v89, v93
	v_add_u32_e32 v101, v89, v94
	v_add_u32_e32 v102, v90, v91
	v_add_u32_e32 v103, v90, v92
	v_add_u32_e32 v104, v90, v93
	v_add_u32_e32 v105, v90, v94
	v_lshl_add_u64 v[72:73], v[68:69], 0, v[66:67]
	v_lshl_add_u64 v[74:75], v[70:71], 0, v[66:67]
	v_readfirstlane_b32 s100, v65
	s_mov_b64 s[44:45], 0x80
	s_add_u32 m0, s100, 0x4000
	v_lshl_add_u64 v[106:107], v[72:73], 0, s[96:97]
	global_load_lds_dwordx4 v[106:107], off
	s_add_u32 m0, s100, 0x5000
	v_lshl_add_u64 v[106:107], v[72:73], 0, s[50:51]
	global_load_lds_dwordx4 v[106:107], off
	s_add_u32 m0, s100, 0x6000
	v_lshl_add_u64 v[106:107], v[72:73], 0, s[24:25]
	global_load_lds_dwordx4 v[106:107], off
	s_add_u32 m0, s100, 0x7000
	v_lshl_add_u64 v[106:107], v[72:73], 0, s[26:27]
	global_load_lds_dwordx4 v[106:107], off
	v_lshl_add_u64 v[72:73], v[72:73], 0, s[44:45]
	s_waitcnt vmcnt(4) lgkmcnt(0)
	s_barrier
	ds_read_b128 v[240:243], v102 offset:32768
	ds_read_b128 v[244:247], v102 offset:36864
	ds_read_b128 v[224:227], v98
	ds_read_b128 v[228:231], v98 offset:4096
	s_mov_b32 s101, 0

; template <int EPI, int MI>
; DI void gemm_tile(const GemmDesc& g, int tm, int tn, char* smem) {
;     ...
;   const int tid = get_tid(), lane = tid & 63, wave = tid >> 6, r = lane & 31, hh = lane >> 5;
;   const int wm = wave >> 1, wn = wave & 1;
;   const int m0 = tm * BM, n0 = tn * 128;
;   const int nk = g.K >> 6;
;   f32x16 acc[MI][2];
; #pragma unroll
;   for (int a = 0; a < MI; ++a)
; #pragma unroll
;     for (int b = 0; b < 2; ++b)
; #pragma unroll
;       for (int i = 0; i < 16; ++i) acc[a][b][i] = 0.f;
;   const int srow = tid >> 3;
;   const int schunk = (tid & 7) ^ ((srow & 7) ^ ((srow >> 3) & 3));
;     ...
;   const int rowA = wm * (32 * MI) + r, rowB = wn * 64 + r;
;   const int hk = hh ^ ((r & 7) ^ ((r >> 3) & 3));
;     ...
;   G_GLDS(0, 0);
;   asm volatile("s_waitcnt vmcnt(0)" ::: "memory");
;   __syncthreads();
; template <int EPI, int MI>
; DI void gemm_phase(const GemmDesc& g, char* smem, int vb, int nvb) {
;     ...
;   for (int q = start; q < local; q += step) {
;     const int mg = q / per;
;     const int rem = q - mg * per;
;     const int tn = rem / PM;
;     const int tm = mbase + mg * PM + (rem - tn * PM);
.LBB0_1421:
	s_abs_i32 s1, s5
	v_readlane_b32 s15, v219, 45
	s_mul_hi_u32 s15, s1, s15
	v_readlane_b32 s18, v219, 44
	s_mul_i32 s16, s15, s18
	s_sub_i32 s1, s1, s16
	s_ashr_i32 s0, s5, 31
	s_add_i32 s16, s15, 1
	s_sub_i32 s17, s1, s18
	s_cmp_ge_u32 s1, s18
	s_cselect_b32 s15, s16, s15
	s_cselect_b32 s1, s17, s1
	s_add_i32 s16, s15, 1
	s_cmp_ge_u32 s1, s18
	s_cselect_b32 s1, s16, s15
	s_xor_b32 s1, s1, s0
	s_sub_i32 s15, s1, s0
	s_mul_i32 s16, s15, s18
	s_sub_i32 s16, s5, s16
	s_abs_i32 s18, s16
	v_readlane_b32 s19, v219, 46
	s_mul_hi_u32 s19, s18, s19
	v_readlane_b32 s40, v218, 32
	s_mul_i32 s38, s19, s40
	s_sub_i32 s18, s18, s38
	s_ashr_i32 s17, s16, 31
	s_add_i32 s38, s19, 1
	s_sub_i32 s39, s18, s40
	s_cmp_ge_u32 s18, s40
	s_cselect_b32 s19, s38, s19
	s_cselect_b32 s18, s39, s18
	s_add_i32 s38, s19, 1
	s_cmp_ge_u32 s18, s40
	s_cselect_b32 s18, s38, s19
	s_xor_b32 s18, s18, s17
	s_sub_i32 s39, s18, s17
	s_sub_i32 s15, s15, s39
	v_mov_b32_e32 v6, v132
	s_mul_i32 s15, s15, s40
	s_add_i32 s16, s16, s54
	s_add_i32 s38, s16, s15
	v_ashrrev_i32_e32 v97, 3, v6
	v_ashrrev_i32_e32 v120, 7, v6
	v_bfe_u32 v0, v6, 6, 2
	v_xor_b32_e32 v1, v97, v6
	s_mulk_i32 s38, 0xc0
	v_and_b32_e32 v121, 31, v6
	v_bitop3_b32 v2, v1, v0, 7 bitop3:0x6c
	v_mul_lo_u32 v0, v120, s6
	v_and_b32_e32 v115, 7, v6
	v_or_b32_e32 v8, v0, v121
	v_lshrrev_b32_e32 v0, 3, v6
	s_waitcnt vmcnt(10)
	v_add_u32_e32 v98, s38, v97
	v_bfe_u32 v122, v6, 5, 1
	v_bitop3_b32 v0, v0, v115, 3 bitop3:0x6c
	v_ashrrev_i32_e32 v99, 31, v98
	v_readlane_b32 s40, v223, 59
	v_xor_b32_e32 v9, v0, v122
	v_lshlrev_b64 v[0:1], 11, v[98:99]
	v_readlane_b32 s41, v223, 60
	v_lshlrev_b32_e32 v100, 4, v2
	v_lshl_add_u32 v2, s39, 7, v97
	v_lshlrev_b32_e32 v99, 4, v6
	v_lshl_add_u64 v[0:1], s[40:41], 0, v[0:1]
	v_ashrrev_i32_e32 v3, 31, v2
	v_readlane_b32 s40, v220, 54
	v_add_u32_e32 v124, 0, v99
	v_mov_b32_e32 v101, v96
	v_lshlrev_b64 v[2:3], 11, v[2:3]
	v_readlane_b32 s41, v220, 55
	v_readfirstlane_b32 s15, v124
	v_add_u32_e32 v125, 0x1000, v124
	v_lshl_add_u64 v[0:1], v[0:1], 0, v[100:101]
	v_lshl_add_u64 v[4:5], s[40:41], 0, v[2:3]
	s_mov_b32 m0, s15
	s_mov_b64 s[40:41], 0x10000
	v_readfirstlane_b32 s15, v125
	v_add_u32_e32 v126, 0x2000, v124
	v_bfe_u32 v123, v6, 6, 1
	global_load_lds_dwordx4 v[0:1], off
	v_lshl_add_u64 v[6:7], v[0:1], 0, s[40:41]
	s_mov_b32 m0, s15
	s_mov_b64 s[42:43], 0x20000
	v_readfirstlane_b32 s15, v126
	v_add_u32_e32 v127, 0x3000, v124
	global_load_lds_dwordx4 v[6:7], off
	v_lshl_add_u64 v[6:7], v[0:1], 0, s[42:43]
	s_mov_b32 m0, s15
	s_mov_b64 s[44:45], 0x30000
	v_readfirstlane_b32 s15, v127
	v_add_u32_e32 v128, 0x4000, v124
	global_load_lds_dwordx4 v[6:7], off
	v_lshl_add_u64 v[6:7], v[0:1], 0, s[44:45]
	s_mov_b32 m0, s15
	s_mov_b64 s[46:47], 0x40000
	v_readfirstlane_b32 s15, v128
	v_add_u32_e32 v129, 0x5000, v124
	global_load_lds_dwordx4 v[6:7], off
	v_lshl_add_u64 v[6:7], v[0:1], 0, s[46:47]
	s_mov_b32 m0, s15
	s_mov_b64 s[46:47], 0x50000
	v_readfirstlane_b32 s15, v129
	v_add_u32_e32 v130, 0xc000, v124
	global_load_lds_dwordx4 v[6:7], off
	v_lshl_add_u64 v[0:1], v[0:1], 0, s[46:47]
	s_mov_b32 m0, s15
	v_readfirstlane_b32 s15, v130
	v_add_u32_e32 v131, 0xd000, v124
	global_load_lds_dwordx4 v[0:1], off
	v_lshl_add_u64 v[0:1], v[4:5], 0, v[100:101]
	s_mov_b32 m0, s15
	v_readfirstlane_b32 s15, v131
	v_add_u32_e32 v153, 0xe000, v124
	global_load_lds_dwordx4 v[0:1], off
	v_lshl_add_u64 v[4:5], v[0:1], 0, s[40:41]
	s_mov_b32 m0, s15
	v_readfirstlane_b32 s15, v153
	v_add_u32_e32 v154, 0xf000, v124
	global_load_lds_dwordx4 v[4:5], off
	v_lshl_add_u64 v[4:5], v[0:1], 0, s[42:43]
	s_mov_b32 m0, s15
	v_readfirstlane_b32 s15, v154
	global_load_lds_dwordx4 v[4:5], off
	v_lshl_add_u64 v[0:1], v[0:1], 0, s[44:45]
	s_mov_b32 m0, s15
	s_mul_i32 s0, s0, 43
	global_load_lds_dwordx4 v[0:1], off
	s_add_i32 s17, s17, s0
	s_sub_i32 s0, s17, s18
	s_mul_i32 s1, s1, 43
	s_sub_i32 s0, s0, s1
	v_readlane_b32 s1, v218, 33
	v_lshlrev_b32_e32 v0, 7, v121
	s_mul_i32 s0, s1, s0
	v_lshl_or_b32 v0, v123, 13, v0
	s_add_i32 s0, s0, s4
	v_add_u32_e32 v156, 0, v0
	v_add_u32_e32 v158, s10, v0
	v_add_u32_e32 v0, s0, v97
	v_ashrrev_i32_e32 v1, 31, v0
	s_waitcnt vmcnt(0)
	v_lshlrev_b64 v[0:1], 11, v[0:1]
	v_lshlrev_b32_e32 v157, 4, v9
	s_waitcnt vmcnt(0)
; template <int EPI, int MI>
; DI void gemm_tile(const GemmDesc& g, int tm, int tn, char* smem) {
;     ...
;   f32x16 acc[MI][2];
; #pragma unroll
;   for (int a = 0; a < MI; ++a)
; #pragma unroll
;     for (int b = 0; b < 2; ++b)
; #pragma unroll
;       for (int i = 0; i < 16; ++i) acc[a][b][i] = 0.f;
;   const int srow = tid >> 3;
;   const int schunk = (tid & 7) ^ ((srow & 7) ^ ((srow >> 3) & 3));
;     ...
;   const int rowA = wm * (32 * MI) + r, rowB = wn * 64 + r;
;   const int hk = hh ^ ((r & 7) ^ ((r >> 3) & 3));
;     ...
;   G_GLDS(0, 0);
;   asm volatile("s_waitcnt vmcnt(0)" ::: "memory");
;   __syncthreads();
;   for (int kt = 0; kt < nk; kt += 2) {
;     if (kt + 1 < nk) G_GLDS(kt + 1, 1);
	v_lshl_add_u64 v[102:103], s[70:71], 0, v[0:1]
	v_mov_b32_e32 v0, 0
	v_lshl_add_u32 v155, v8, 7, 0
	v_xor_b32_e32 v159, 32, v157
	v_xor_b32_e32 v160, 64, v157
	v_xor_b32_e32 v161, 0x60, v157
	v_lshl_add_u64 v[104:105], s[70:71], 0, v[2:3]
	s_mov_b32 s15, 0
	v_mov_b32_e32 v1, v0
	v_mov_b32_e32 v2, v0
	v_mov_b32_e32 v3, v0
	v_mov_b32_e32 v4, v0
	v_mov_b32_e32 v5, v0
	v_mov_b32_e32 v6, v0
	v_mov_b32_e32 v7, v0
	v_mov_b32_e32 v8, v0
	v_mov_b32_e32 v9, v0
	v_mov_b32_e32 v10, v0
	v_mov_b32_e32 v11, v0
	v_mov_b32_e32 v12, v0
	v_mov_b32_e32 v13, v0
	v_mov_b32_e32 v14, v0
	v_mov_b32_e32 v15, v0
	v_mov_b32_e32 v16, v0
	v_mov_b32_e32 v17, v0
	v_mov_b32_e32 v18, v0
	v_mov_b32_e32 v19, v0
	v_mov_b32_e32 v20, v0
	v_mov_b32_e32 v21, v0
	v_mov_b32_e32 v22, v0
	v_mov_b32_e32 v23, v0
	v_mov_b32_e32 v24, v0
	v_mov_b32_e32 v25, v0
	v_mov_b32_e32 v26, v0
	v_mov_b32_e32 v27, v0
	v_mov_b32_e32 v28, v0
	v_mov_b32_e32 v29, v0
	v_mov_b32_e32 v30, v0
	v_mov_b32_e32 v31, v0
	v_mov_b32_e32 v32, v0
	v_mov_b32_e32 v33, v0
	v_mov_b32_e32 v34, v0
	v_mov_b32_e32 v35, v0
	v_mov_b32_e32 v36, v0
	v_mov_b32_e32 v37, v0
	v_mov_b32_e32 v38, v0
	v_mov_b32_e32 v39, v0
	v_mov_b32_e32 v40, v0
	v_mov_b32_e32 v41, v0
	v_mov_b32_e32 v42, v0
	v_mov_b32_e32 v43, v0
	v_mov_b32_e32 v44, v0
	v_mov_b32_e32 v45, v0
	v_mov_b32_e32 v46, v0
	v_mov_b32_e32 v47, v0
	v_mov_b32_e32 v48, v0
	v_mov_b32_e32 v49, v0
	v_mov_b32_e32 v50, v0
	v_mov_b32_e32 v51, v0
	v_mov_b32_e32 v52, v0
	v_mov_b32_e32 v53, v0
	v_mov_b32_e32 v54, v0
	v_mov_b32_e32 v55, v0
	v_mov_b32_e32 v56, v0
	v_mov_b32_e32 v57, v0
	v_mov_b32_e32 v58, v0
	v_mov_b32_e32 v59, v0
	v_mov_b32_e32 v60, v0
	v_mov_b32_e32 v61, v0
	v_mov_b32_e32 v62, v0
	v_mov_b32_e32 v63, v0
	v_mov_b32_e32 v64, v0
	v_mov_b32_e32 v65, v0
	v_mov_b32_e32 v66, v0
	v_mov_b32_e32 v67, v0
	v_mov_b32_e32 v68, v0
	v_mov_b32_e32 v69, v0
	v_mov_b32_e32 v70, v0
	v_mov_b32_e32 v71, v0
	v_mov_b32_e32 v72, v0
	v_mov_b32_e32 v73, v0
	v_mov_b32_e32 v74, v0
	v_mov_b32_e32 v75, v0
	v_mov_b32_e32 v76, v0
	v_mov_b32_e32 v77, v0
	v_mov_b32_e32 v78, v0
	v_mov_b32_e32 v79, v0
	v_mov_b32_e32 v80, v0
	v_mov_b32_e32 v81, v0
	v_mov_b32_e32 v82, v0
	v_mov_b32_e32 v83, v0
	v_mov_b32_e32 v84, v0
	v_mov_b32_e32 v85, v0
	v_mov_b32_e32 v86, v0
	v_mov_b32_e32 v87, v0
	v_mov_b32_e32 v88, v0
	v_mov_b32_e32 v89, v0
	v_mov_b32_e32 v90, v0
	v_mov_b32_e32 v91, v0
	v_mov_b32_e32 v92, v0
	v_mov_b32_e32 v93, v0
	v_mov_b32_e32 v94, v0
	v_mov_b32_e32 v95, v0
	v_add_u32_e32 v162, v155, v157
	v_add_u32_e32 v163, v155, v159
	v_add_u32_e32 v164, v155, v160
	v_add_u32_e32 v165, v155, v161
	v_add_u32_e32 v166, v156, v157
	v_add_u32_e32 v167, v156, v159
	v_add_u32_e32 v168, v156, v160
	v_add_u32_e32 v169, v156, v161
	v_add_u32_e32 v170, v158, v157
	v_add_u32_e32 v171, v158, v159
	v_add_u32_e32 v172, v158, v160
	v_add_u32_e32 v173, v158, v161
	v_lshl_add_u64 v[252:253], v[102:103], 0, v[100:101]
	v_lshl_add_u64 v[254:255], v[104:105], 0, v[100:101]
	v_readfirstlane_b32 s100, v124
	s_mov_b64 s[0:1], 0x80
	s_add_u32 m0, s100, 0x6000
	v_lshl_add_u64 v[106:107], v[252:253], 0, s[96:97]
	global_load_lds_dwordx4 v[106:107], off
	s_add_u32 m0, s100, 0x7000
	v_lshl_add_u64 v[106:107], v[252:253], 0, s[50:51]
	global_load_lds_dwordx4 v[106:107], off
	s_add_u32 m0, s100, 0x8000
	v_lshl_add_u64 v[106:107], v[252:253], 0, s[24:25]
	global_load_lds_dwordx4 v[106:107], off
	s_add_u32 m0, s100, 0x9000
	v_lshl_add_u64 v[106:107], v[252:253], 0, s[26:27]
	global_load_lds_dwordx4 v[106:107], off
	s_add_u32 m0, s100, 0xa000
	v_lshl_add_u64 v[106:107], v[252:253], 0, s[28:29]
	global_load_lds_dwordx4 v[106:107], off
	s_add_u32 m0, s100, 0xb000
	v_lshl_add_u64 v[106:107], v[252:253], 0, s[30:31]
	global_load_lds_dwordx4 v[106:107], off
	v_lshl_add_u64 v[252:253], v[252:253], 0, s[0:1]
	s_mov_b64 s[16:17], 0xb00080
	s_add_u32 m0, s100, 0x10000
	v_lshl_add_u64 v[106:107], v[254:255], 0, s[16:17]
	global_load_lds_dwordx4 v[106:107], off
	s_mov_b64 s[16:17], 0xb10080
	s_add_u32 m0, s100, 0x11000
	v_lshl_add_u64 v[106:107], v[254:255], 0, s[16:17]
	global_load_lds_dwordx4 v[106:107], off
	s_mov_b64 s[16:17], 0xb20080
	s_add_u32 m0, s100, 0x12000
	v_lshl_add_u64 v[106:107], v[254:255], 0, s[16:17]
	global_load_lds_dwordx4 v[106:107], off
	s_mov_b64 s[16:17], 0xb30080
	s_add_u32 m0, s100, 0x13000
	v_lshl_add_u64 v[106:107], v[254:255], 0, s[16:17]
	global_load_lds_dwordx4 v[106:107], off
	v_lshl_add_u64 v[254:255], v[254:255], 0, s[0:1]
	s_waitcnt vmcnt(10) lgkmcnt(0)
	s_barrier
	ds_read_b128 v[236:239], v166 offset:49152
	ds_read_b128 v[240:243], v166 offset:53248
	ds_read_b128 v[224:227], v162
	ds_read_b128 v[228:231], v162 offset:4096
	s_mov_b32 s101, 0

; template <int EPI, int MI>
; DI void gemm_tile(const GemmDesc& g, int tm, int tn, char* smem) {
;     ...
;   const int tid = get_tid(), lane = tid & 63, wave = tid >> 6, r = lane & 31, hh = lane >> 5;
;   const int wm = wave >> 1, wn = wave & 1;
;   const int m0 = tm * BM, n0 = tn * 128;
;   const int nk = g.K >> 6;
;   f32x16 acc[MI][2];
; #pragma unroll
;   for (int a = 0; a < MI; ++a)
; #pragma unroll
;     for (int b = 0; b < 2; ++b)
; #pragma unroll
;       for (int i = 0; i < 16; ++i) acc[a][b][i] = 0.f;
;   const int srow = tid >> 3;
;   const int schunk = (tid & 7) ^ ((srow & 7) ^ ((srow >> 3) & 3));
;     ...
;   const int rowA = wm * (32 * MI) + r, rowB = wn * 64 + r;
;   const int hk = hh ^ ((r & 7) ^ ((r >> 3) & 3));
;     ...
;   G_GLDS(0, 0);
;   asm volatile("s_waitcnt vmcnt(0)" ::: "memory");
;   __syncthreads();
;   for (int kt = 0; kt < nk; kt += 2) {
;     if (kt + 1 < nk) G_GLDS(kt + 1, 1);
; template <int EPI, int MI>
; DI void gemm_phase(const GemmDesc& g, char* smem, int vb, int nvb) {
;     ...
;   for (int q = start; q < local; q += step) {
;     const int mg = q / per;
;     const int rem = q - mg * per;
;     const int tn = rem / PM;
;     const int tm = mbase + mg * PM + (rem - tn * PM);
.LBB0_1478:
	s_abs_i32 s0, s44
	s_mul_hi_u32 s1, s0, s42
	s_mul_i32 s4, s1, s38
	s_sub_i32 s0, s0, s4
	s_ashr_i32 s18, s44, 31
	s_add_i32 s4, s1, 1
	s_sub_i32 s5, s0, s38
	s_cmp_ge_u32 s0, s38
	s_cselect_b32 s1, s4, s1
	s_cselect_b32 s0, s5, s0
	s_add_i32 s4, s1, 1
	s_cmp_ge_u32 s0, s38
	s_cselect_b32 s0, s4, s1
	s_xor_b32 s19, s0, s18
	s_sub_i32 s0, s19, s18
	s_mul_i32 s1, s0, s38
	s_sub_i32 s1, s44, s1
	s_abs_i32 s4, s1
	s_mul_hi_u32 s5, s4, s16
	s_mul_i32 s45, s5, s15
	s_sub_i32 s4, s4, s45
	s_ashr_i32 s46, s1, 31
	s_add_i32 s45, s5, 1
	s_sub_i32 s47, s4, s15
	s_cmp_ge_u32 s4, s15
	s_cselect_b32 s5, s45, s5
	s_cselect_b32 s4, s47, s4
	s_add_i32 s45, s5, 1
	s_cmp_ge_u32 s4, s15
	s_cselect_b32 s4, s45, s5
	s_xor_b32 s47, s4, s46
	s_sub_i32 s4, s47, s46
	v_mov_b32_e32 v75, v132
	s_mul_i32 s0, s0, s15
	s_mul_i32 s5, s4, s15
	s_add_i32 s0, s0, s39
	v_ashrrev_i32_e32 v6, 3, v75
	s_sub_i32 s1, s1, s5
	v_bfe_u32 v1, v75, 6, 2
	v_xor_b32_e32 v2, v6, v75
	s_add_i32 s1, s0, s1
	s_lshl_b32 s0, s4, 7
	v_and_b32_e32 v0, 7, v75
	v_bitop3_b32 v2, v2, v1, 7 bitop3:0x6c
	v_lshrrev_b32_e32 v1, 3, v75
	v_readlane_b32 s4, v221, 5
	s_lshl_b32 s45, s1, 7
	v_bfe_u32 v77, v75, 5, 1
	v_bitop3_b32 v0, v1, v0, 3 bitop3:0x6c
	v_readlane_b32 s5, v221, 6
	v_xor_b32_e32 v7, v0, v77
	v_add_u32_e32 v3, s45, v6
	v_mov_b64_e32 v[0:1], s[4:5]
	s_movk_i32 s52, 0x1600
	v_mad_i64_i32 v[0:1], s[4:5], v3, s52, v[0:1]
	v_readlane_b32 s4, v220, 56
	v_readlane_b32 s5, v220, 57
	v_lshlrev_b32_e32 v64, 4, v2
	v_add_u32_e32 v8, s0, v6
	v_mov_b64_e32 v[2:3], s[4:5]
	v_lshlrev_b32_e32 v4, 4, v75
	v_mad_i64_i32 v[2:3], s[4:5], v8, s52, v[2:3]
	v_add_u32_e32 v78, 0, v4
	v_mov_b32_e32 v65, v96
	v_readfirstlane_b32 s4, v78
	v_add_u32_e32 v79, 0x1000, v78
	v_lshl_add_u64 v[0:1], v[0:1], 0, v[64:65]
	s_mov_b32 m0, s4
	s_mov_b64 s[72:73], 0x2c000
	v_readfirstlane_b32 s4, v79
	v_add_u32_e32 v80, 0x2000, v78
	global_load_lds_dwordx4 v[0:1], off
	v_lshl_add_u64 v[4:5], v[0:1], 0, s[72:73]
	s_mov_b32 m0, s4
	s_mov_b64 s[74:75], 0x58000
	v_readfirstlane_b32 s4, v80
	v_add_u32_e32 v81, 0x3000, v78
	global_load_lds_dwordx4 v[4:5], off
	v_lshl_add_u64 v[4:5], v[0:1], 0, s[74:75]
	s_mov_b32 m0, s4
	s_mov_b64 s[76:77], 0x84000
	v_readfirstlane_b32 s4, v81
	v_add_u32_e32 v82, 0x8000, v78
	global_load_lds_dwordx4 v[4:5], off
	v_lshl_add_u64 v[0:1], v[0:1], 0, s[76:77]
	s_mov_b32 m0, s4
	v_readfirstlane_b32 s4, v82
	v_add_u32_e32 v83, 0x9000, v78
	global_load_lds_dwordx4 v[0:1], off
	v_lshl_add_u64 v[0:1], v[2:3], 0, v[64:65]
	s_mov_b32 m0, s4
	v_readfirstlane_b32 s4, v83
	v_add_u32_e32 v84, 0xa000, v78
	global_load_lds_dwordx4 v[0:1], off
	v_lshl_add_u64 v[2:3], v[0:1], 0, s[72:73]
	s_mov_b32 m0, s4
	v_readfirstlane_b32 s4, v84
	v_add_u32_e32 v85, 0xb000, v78
	global_load_lds_dwordx4 v[2:3], off
	v_lshl_add_u64 v[2:3], v[0:1], 0, s[74:75]
	s_mov_b32 m0, s4
	v_readfirstlane_b32 s4, v85
	global_load_lds_dwordx4 v[2:3], off
	v_lshl_add_u64 v[0:1], v[0:1], 0, s[76:77]
	s_mov_b32 m0, s4
	s_mul_i32 s18, s18, 7
	global_load_lds_dwordx4 v[0:1], off
	v_and_b32_e32 v74, 31, v75
	s_add_i32 s46, s46, s18
	v_ashrrev_i32_e32 v76, 7, v75
	v_lshlrev_b32_e32 v0, 7, v74
	s_sub_i32 s4, s46, s47
	s_mul_i32 s19, s19, 7
	v_lshl_or_b32 v0, v76, 13, v0
	s_sub_i32 s4, s4, s19
	v_add_u32_e32 v86, 0, v0
	v_lshlrev_b32_e32 v0, 7, v75
	s_mul_i32 s4, s43, s4
	v_and_b32_e32 v0, 0x2f80, v0
	s_add_i32 s4, s4, s17
	s_waitcnt vmcnt(0)
	v_add_u32_e32 v87, 0, v0
	v_add_u32_e32 v2, s4, v6
	v_mov_b64_e32 v[0:1], s[70:71]
	s_waitcnt vmcnt(0)
	v_lshlrev_b32_e32 v88, 4, v7
	v_mad_i64_i32 v[66:67], s[4:5], v2, s52, v[0:1]
	v_mad_i64_i32 v[68:69], s[4:5], v8, s52, v[0:1]
	v_mov_b32_e32 v0, 0
	v_xor_b32_e32 v89, 32, v88
	v_xor_b32_e32 v90, 64, v88
	v_xor_b32_e32 v91, 0x60, v88
	s_mov_b32 s18, 0
	v_mov_b32_e32 v1, v0
	v_mov_b32_e32 v2, v0
	v_mov_b32_e32 v3, v0
	v_mov_b32_e32 v4, v0
	v_mov_b32_e32 v5, v0
	v_mov_b32_e32 v6, v0
	v_mov_b32_e32 v7, v0
	v_mov_b32_e32 v8, v0
	v_mov_b32_e32 v9, v0
	v_mov_b32_e32 v10, v0
	v_mov_b32_e32 v11, v0
	v_mov_b32_e32 v12, v0
	v_mov_b32_e32 v13, v0
	v_mov_b32_e32 v14, v0
	v_mov_b32_e32 v15, v0
	v_mov_b32_e32 v16, v0
	v_mov_b32_e32 v17, v0
	v_mov_b32_e32 v18, v0
	v_mov_b32_e32 v19, v0
	v_mov_b32_e32 v20, v0
	v_mov_b32_e32 v21, v0
	v_mov_b32_e32 v22, v0
	v_mov_b32_e32 v23, v0
	v_mov_b32_e32 v24, v0
	v_mov_b32_e32 v25, v0
	v_mov_b32_e32 v26, v0
	v_mov_b32_e32 v27, v0
	v_mov_b32_e32 v28, v0
	v_mov_b32_e32 v29, v0
	v_mov_b32_e32 v30, v0
	v_mov_b32_e32 v31, v0
	v_mov_b32_e32 v32, v0
	v_mov_b32_e32 v33, v0
	v_mov_b32_e32 v34, v0
	v_mov_b32_e32 v35, v0
	v_mov_b32_e32 v36, v0
	v_mov_b32_e32 v37, v0
	v_mov_b32_e32 v38, v0
	v_mov_b32_e32 v39, v0
	v_mov_b32_e32 v40, v0
	v_mov_b32_e32 v41, v0
	v_mov_b32_e32 v42, v0
	v_mov_b32_e32 v43, v0
	v_mov_b32_e32 v44, v0
	v_mov_b32_e32 v45, v0
	v_mov_b32_e32 v46, v0
	v_mov_b32_e32 v47, v0
	v_mov_b32_e32 v48, v0
	v_mov_b32_e32 v49, v0
	v_mov_b32_e32 v50, v0
	v_mov_b32_e32 v51, v0
	v_mov_b32_e32 v52, v0
	v_mov_b32_e32 v53, v0
	v_mov_b32_e32 v54, v0
	v_mov_b32_e32 v55, v0
	v_mov_b32_e32 v56, v0
	v_mov_b32_e32 v57, v0
	v_mov_b32_e32 v58, v0
	v_mov_b32_e32 v59, v0
	v_mov_b32_e32 v60, v0
	v_mov_b32_e32 v61, v0
	v_mov_b32_e32 v62, v0
	v_mov_b32_e32 v63, v0
	v_add_u32_e32 v92, v86, v88
	v_add_u32_e32 v93, v86, v89
	v_add_u32_e32 v94, v86, v90
	v_add_u32_e32 v95, v86, v91
	v_add_u32_e32 v97, v87, v88
	v_add_u32_e32 v98, v87, v89
	v_add_u32_e32 v99, v87, v90
	v_add_u32_e32 v100, v87, v91
	v_lshl_add_u64 v[104:105], v[66:67], 0, v[64:65]
	v_lshl_add_u64 v[106:107], v[68:69], 0, v[64:65]
	v_readfirstlane_b32 s100, v78
	s_mov_b64 s[46:47], 0x80
	s_mov_b64 s[4:5], 0x5872080
	s_add_u32 m0, s100, 0x4000
	v_lshl_add_u64 v[102:103], v[104:105], 0, s[4:5]
	global_load_lds_dwordx4 v[102:103], off
	s_mov_b64 s[4:5], 0x589e080
	s_add_u32 m0, s100, 0x5000
	v_lshl_add_u64 v[102:103], v[104:105], 0, s[4:5]
	global_load_lds_dwordx4 v[102:103], off
	s_mov_b64 s[4:5], 0x58ca080
	s_add_u32 m0, s100, 0x6000
	v_lshl_add_u64 v[102:103], v[104:105], 0, s[4:5]
	global_load_lds_dwordx4 v[102:103], off
	s_mov_b64 s[4:5], 0x58f6080
	s_add_u32 m0, s100, 0x7000
	v_lshl_add_u64 v[102:103], v[104:105], 0, s[4:5]
	global_load_lds_dwordx4 v[102:103], off
	v_lshl_add_u64 v[104:105], v[104:105], 0, s[46:47]
	s_waitcnt vmcnt(4) lgkmcnt(0)
	s_barrier
	ds_read_b128 v[240:243], v97 offset:32768
	ds_read_b128 v[244:247], v97 offset:36864
	ds_read_b128 v[224:227], v92
	ds_read_b128 v[228:231], v92 offset:4096
	s_mov_b32 s101, 0

; template <int EPI, int MI>
; DI void gemm_tile(const GemmDesc& g, int tm, int tn, char* smem) {
;     ...
;   const int tid = get_tid(), lane = tid & 63, wave = tid >> 6, r = lane & 31, hh = lane >> 5;
;   const int wm = wave >> 1, wn = wave & 1;
;   const int m0 = tm * BM, n0 = tn * 128;
;   const int nk = g.K >> 6;
;   f32x16 acc[MI][2];
; #pragma unroll
;   for (int a = 0; a < MI; ++a)
; #pragma unroll
;     for (int b = 0; b < 2; ++b)
; #pragma unroll
;       for (int i = 0; i < 16; ++i) acc[a][b][i] = 0.f;
;   const int srow = tid >> 3;
;   const int schunk = (tid & 7) ^ ((srow & 7) ^ ((srow >> 3) & 3));
;     ...
;   const int rowA = wm * (32 * MI) + r, rowB = wn * 64 + r;
;   const int hk = hh ^ ((r & 7) ^ ((r >> 3) & 3));
;     ...
;   G_GLDS(0, 0);
;   asm volatile("s_waitcnt vmcnt(0)" ::: "memory");
;   __syncthreads();
; template <int EPI, int MI>
; DI void gemm_phase(const GemmDesc& g, char* smem, int vb, int nvb) {
;     ...
;   for (int q = start; q < local; q += step) {
;     const int mg = q / per;
;     const int rem = q - mg * per;
;     const int tn = rem / PM;
;     const int tm = mbase + mg * PM + (rem - tn * PM);
.LBB0_1491:
	s_abs_i32 s0, s40
	v_readlane_b32 s1, v219, 48
	s_mul_hi_u32 s1, s0, s1
	v_readlane_b32 s17, v219, 47
	s_mul_i32 s4, s1, s17
	s_sub_i32 s0, s0, s4
	s_ashr_i32 s15, s40, 31
	s_add_i32 s4, s1, 1
	s_sub_i32 s5, s0, s17
	s_cmp_ge_u32 s0, s17
	s_cselect_b32 s1, s4, s1
	s_cselect_b32 s0, s5, s0
	s_add_i32 s4, s1, 1
	s_cmp_ge_u32 s0, s17
	s_cselect_b32 s0, s4, s1
	s_xor_b32 s16, s0, s15
	s_sub_i32 s0, s16, s15
	s_mul_i32 s1, s0, s17
	s_sub_i32 s1, s40, s1
	s_abs_i32 s4, s1
	v_readlane_b32 s5, v219, 46
	s_mul_hi_u32 s5, s4, s5
	v_readlane_b32 s41, v218, 32
	s_mul_i32 s18, s5, s41
	s_sub_i32 s4, s4, s18
	s_ashr_i32 s17, s1, 31
	s_add_i32 s18, s5, 1
	s_sub_i32 s19, s4, s41
	s_cmp_ge_u32 s4, s41
	s_cselect_b32 s5, s18, s5
	s_cselect_b32 s4, s19, s4
	s_add_i32 s18, s5, 1
	s_cmp_ge_u32 s4, s41
	s_cselect_b32 s4, s18, s5
	s_xor_b32 s18, s4, s17
	v_mov_b32_e32 v97, v132
	s_sub_i32 s4, s18, s17
	s_mul_i32 s0, s0, s41
	v_ashrrev_i32_e32 v6, 3, v97
	s_mul_i32 s5, s4, s41
	s_waitcnt vmcnt(8)
	v_ashrrev_i32_e32 v109, 7, v97
	v_bfe_u32 v1, v97, 6, 2
	v_xor_b32_e32 v2, v6, v97
	s_add_i32 s0, s0, s54
	s_sub_i32 s1, s1, s5
	v_and_b32_e32 v108, 31, v97
	v_bitop3_b32 v2, v2, v1, 7 bitop3:0x6c
	v_mul_lo_u32 v1, v109, s6
	s_add_i32 s1, s0, s1
	s_lshl_b32 s0, s4, 7
	v_and_b32_e32 v0, 7, v97
	v_or_b32_e32 v7, v1, v108
	v_lshrrev_b32_e32 v1, 3, v97
	v_readlane_b32 s4, v221, 5
	s_mul_i32 s41, s1, 0xc0
	v_bfe_u32 v115, v97, 5, 1
	v_bitop3_b32 v0, v1, v0, 3 bitop3:0x6c
	v_readlane_b32 s5, v221, 6
	v_xor_b32_e32 v8, v0, v115
	v_add_u32_e32 v3, s41, v6
	v_mov_b64_e32 v[0:1], s[4:5]
	s_movk_i32 s19, 0x1600
	v_mad_i64_i32 v[0:1], s[4:5], v3, s19, v[0:1]
	v_readlane_b32 s4, v220, 56
	v_readlane_b32 s5, v220, 57
	v_lshlrev_b32_e32 v98, 4, v2
	v_add_u32_e32 v9, s0, v6
	v_mov_b64_e32 v[2:3], s[4:5]
	v_lshlrev_b32_e32 v120, 4, v97
	v_mad_i64_i32 v[2:3], s[4:5], v9, s19, v[2:3]
	v_add_u32_e32 v121, 0, v120
	v_mov_b32_e32 v99, v96
	v_readfirstlane_b32 s4, v121
	v_add_u32_e32 v122, 0x1000, v121
	v_lshl_add_u64 v[0:1], v[0:1], 0, v[98:99]
	s_mov_b32 m0, s4
	s_mov_b64 s[42:43], 0x2c000
	v_readfirstlane_b32 s4, v122
	v_add_u32_e32 v123, 0x2000, v121
	global_load_lds_dwordx4 v[0:1], off
	v_lshl_add_u64 v[4:5], v[0:1], 0, s[42:43]
	s_mov_b32 m0, s4
	s_mov_b64 s[44:45], 0x58000
	v_readfirstlane_b32 s4, v123
	v_add_u32_e32 v124, 0x3000, v121
	global_load_lds_dwordx4 v[4:5], off
	v_lshl_add_u64 v[4:5], v[0:1], 0, s[44:45]
	s_mov_b32 m0, s4
	s_mov_b64 s[46:47], 0x84000
	v_readfirstlane_b32 s4, v124
	global_load_lds_dwordx4 v[4:5], off
	v_lshl_add_u64 v[4:5], v[0:1], 0, s[46:47]
	s_mov_b32 m0, s4
	s_mov_b64 s[4:5], 0xb0000
	v_add_u32_e32 v125, 0x4000, v121
	global_load_lds_dwordx4 v[4:5], off
	v_lshl_add_u64 v[4:5], v[0:1], 0, s[4:5]
	v_readfirstlane_b32 s4, v125
	s_mov_b32 m0, s4
	s_mov_b64 s[4:5], 0xdc000
	v_add_u32_e32 v126, 0x5000, v121
	v_lshl_add_u64 v[0:1], v[0:1], 0, s[4:5]
	v_readfirstlane_b32 s4, v126
	v_add_u32_e32 v127, 0xc000, v121
	global_load_lds_dwordx4 v[4:5], off
	s_mov_b32 m0, s4
	v_readfirstlane_b32 s4, v127
	v_add_u32_e32 v128, 0xd000, v121
	global_load_lds_dwordx4 v[0:1], off
	v_lshl_add_u64 v[0:1], v[2:3], 0, v[98:99]
	s_mov_b32 m0, s4
	v_readfirstlane_b32 s4, v128
	v_add_u32_e32 v129, 0xe000, v121
	global_load_lds_dwordx4 v[0:1], off
	v_lshl_add_u64 v[2:3], v[0:1], 0, s[42:43]
	s_mov_b32 m0, s4
	v_readfirstlane_b32 s4, v129
	v_add_u32_e32 v130, 0xf000, v121
	global_load_lds_dwordx4 v[2:3], off
	v_lshl_add_u64 v[2:3], v[0:1], 0, s[44:45]
	s_mov_b32 m0, s4
	v_readfirstlane_b32 s4, v130
	global_load_lds_dwordx4 v[2:3], off
	v_lshl_add_u64 v[0:1], v[0:1], 0, s[46:47]
	s_mov_b32 m0, s4
	s_mul_i32 s15, s15, 7
	global_load_lds_dwordx4 v[0:1], off
	s_add_i32 s17, s17, s15
	s_sub_i32 s4, s17, s18
	s_mul_i32 s16, s16, 7
	s_sub_i32 s4, s4, s16
	v_readlane_b32 s5, v218, 33
	v_lshlrev_b32_e32 v0, 7, v97
	s_mul_i32 s4, s5, s4
	v_and_b32_e32 v0, 0x2f80, v0
	s_add_i32 s4, s4, s39
	s_waitcnt vmcnt(0)
; template <int EPI, int MI>
; DI void gemm_tile(const GemmDesc& g, int tm, int tn, char* smem) {
;     ...
;   f32x16 acc[MI][2];
; #pragma unroll
;   for (int a = 0; a < MI; ++a)
; #pragma unroll
;     for (int b = 0; b < 2; ++b)
; #pragma unroll
;       for (int i = 0; i < 16; ++i) acc[a][b][i] = 0.f;
;   const int srow = tid >> 3;
;   const int schunk = (tid & 7) ^ ((srow & 7) ^ ((srow >> 3) & 3));
;     ...
;   const int rowA = wm * (32 * MI) + r, rowB = wn * 64 + r;
;   const int hk = hh ^ ((r & 7) ^ ((r >> 3) & 3));
;     ...
;   G_GLDS(0, 0);
;   asm volatile("s_waitcnt vmcnt(0)" ::: "memory");
;   __syncthreads();
;   for (int kt = 0; kt < nk; kt += 2) {
;     if (kt + 1 < nk) G_GLDS(kt + 1, 1);
	v_add_u32_e32 v153, 0, v0
	v_add_u32_e32 v155, s10, v0
	v_add_u32_e32 v2, s4, v6
	v_mov_b64_e32 v[0:1], s[70:71]
	v_lshlrev_b32_e32 v154, 4, v8
	v_mad_i64_i32 v[100:101], s[4:5], v2, s19, v[0:1]
	v_mad_i64_i32 v[102:103], s[4:5], v9, s19, v[0:1]
	v_mov_b32_e32 v0, 0
	v_lshl_add_u32 v131, v7, 7, 0
	v_xor_b32_e32 v156, 32, v154
	v_xor_b32_e32 v157, 64, v154
	v_xor_b32_e32 v158, 0x60, v154
	s_mov_b32 s15, 0
	v_mov_b32_e32 v1, v0
	v_mov_b32_e32 v2, v0
	v_mov_b32_e32 v3, v0
	v_mov_b32_e32 v4, v0
	v_mov_b32_e32 v5, v0
	v_mov_b32_e32 v6, v0
	v_mov_b32_e32 v7, v0
	v_mov_b32_e32 v8, v0
	v_mov_b32_e32 v9, v0
	v_mov_b32_e32 v10, v0
	v_mov_b32_e32 v11, v0
	v_mov_b32_e32 v12, v0
	v_mov_b32_e32 v13, v0
	v_mov_b32_e32 v14, v0
	v_mov_b32_e32 v15, v0
	v_mov_b32_e32 v16, v0
	v_mov_b32_e32 v17, v0
	v_mov_b32_e32 v18, v0
	v_mov_b32_e32 v19, v0
	v_mov_b32_e32 v20, v0
	v_mov_b32_e32 v21, v0
	v_mov_b32_e32 v22, v0
	v_mov_b32_e32 v23, v0
	v_mov_b32_e32 v24, v0
	v_mov_b32_e32 v25, v0
	v_mov_b32_e32 v26, v0
	v_mov_b32_e32 v27, v0
	v_mov_b32_e32 v28, v0
	v_mov_b32_e32 v29, v0
	v_mov_b32_e32 v30, v0
	v_mov_b32_e32 v31, v0
	v_mov_b32_e32 v32, v0
	v_mov_b32_e32 v33, v0
	v_mov_b32_e32 v34, v0
	v_mov_b32_e32 v35, v0
	v_mov_b32_e32 v36, v0
	v_mov_b32_e32 v37, v0
	v_mov_b32_e32 v38, v0
	v_mov_b32_e32 v39, v0
	v_mov_b32_e32 v40, v0
	v_mov_b32_e32 v41, v0
	v_mov_b32_e32 v42, v0
	v_mov_b32_e32 v43, v0
	v_mov_b32_e32 v44, v0
	v_mov_b32_e32 v45, v0
	v_mov_b32_e32 v46, v0
	v_mov_b32_e32 v47, v0
	v_mov_b32_e32 v48, v0
	s_waitcnt vmcnt(0)
	v_mov_b32_e32 v49, v0
	v_mov_b32_e32 v50, v0
	v_mov_b32_e32 v51, v0
	v_mov_b32_e32 v52, v0
	v_mov_b32_e32 v53, v0
	v_mov_b32_e32 v54, v0
	v_mov_b32_e32 v55, v0
	v_mov_b32_e32 v56, v0
	v_mov_b32_e32 v57, v0
	v_mov_b32_e32 v58, v0
	v_mov_b32_e32 v59, v0
	v_mov_b32_e32 v60, v0
	v_mov_b32_e32 v61, v0
	v_mov_b32_e32 v62, v0
	v_mov_b32_e32 v63, v0
	v_mov_b32_e32 v64, v0
	v_mov_b32_e32 v65, v0
	v_mov_b32_e32 v66, v0
	v_mov_b32_e32 v67, v0
	v_mov_b32_e32 v68, v0
	v_mov_b32_e32 v69, v0
	v_mov_b32_e32 v70, v0
	v_mov_b32_e32 v71, v0
	v_mov_b32_e32 v72, v0
	v_mov_b32_e32 v73, v0
	v_mov_b32_e32 v74, v0
	v_mov_b32_e32 v75, v0
	v_mov_b32_e32 v76, v0
	v_mov_b32_e32 v77, v0
	v_mov_b32_e32 v78, v0
	v_mov_b32_e32 v79, v0
	v_mov_b32_e32 v80, v0
	v_mov_b32_e32 v81, v0
	v_mov_b32_e32 v82, v0
	v_mov_b32_e32 v83, v0
	v_mov_b32_e32 v84, v0
	v_mov_b32_e32 v85, v0
	v_mov_b32_e32 v86, v0
	v_mov_b32_e32 v87, v0
	v_mov_b32_e32 v88, v0
	v_mov_b32_e32 v89, v0
	v_mov_b32_e32 v90, v0
	v_mov_b32_e32 v91, v0
	v_mov_b32_e32 v92, v0
	v_mov_b32_e32 v93, v0
	v_mov_b32_e32 v94, v0
	v_mov_b32_e32 v95, v0
	v_add_u32_e32 v162, v131, v154
	v_add_u32_e32 v163, v131, v156
	v_add_u32_e32 v164, v131, v157
	v_add_u32_e32 v165, v131, v158
	v_add_u32_e32 v166, v153, v154
	v_add_u32_e32 v167, v153, v156
	v_add_u32_e32 v168, v153, v157
	v_add_u32_e32 v169, v153, v158
	v_add_u32_e32 v170, v155, v154
	v_add_u32_e32 v171, v155, v156
	v_add_u32_e32 v172, v155, v157
	v_add_u32_e32 v173, v155, v158
	v_lshl_add_u64 v[252:253], v[100:101], 0, v[98:99]
	v_lshl_add_u64 v[254:255], v[102:103], 0, v[98:99]
	v_readfirstlane_b32 s100, v121
	s_mov_b64 s[4:5], 0x80
	s_mov_b64 s[16:17], 0x5872080
	s_add_u32 m0, s100, 0x6000
	v_lshl_add_u64 v[106:107], v[252:253], 0, s[16:17]
	global_load_lds_dwordx4 v[106:107], off
	s_mov_b64 s[16:17], 0x589e080
	s_add_u32 m0, s100, 0x7000
	v_lshl_add_u64 v[106:107], v[252:253], 0, s[16:17]
	global_load_lds_dwordx4 v[106:107], off
	s_mov_b64 s[16:17], 0x58ca080
	s_add_u32 m0, s100, 0x8000
	v_lshl_add_u64 v[106:107], v[252:253], 0, s[16:17]
	global_load_lds_dwordx4 v[106:107], off
	s_mov_b64 s[16:17], 0x58f6080
	s_add_u32 m0, s100, 0x9000
	v_lshl_add_u64 v[106:107], v[252:253], 0, s[16:17]
	global_load_lds_dwordx4 v[106:107], off
	s_mov_b64 s[16:17], 0x5922080
	s_add_u32 m0, s100, 0xa000
	v_lshl_add_u64 v[106:107], v[252:253], 0, s[16:17]
	global_load_lds_dwordx4 v[106:107], off
	s_mov_b64 s[16:17], 0x594e080
	s_add_u32 m0, s100, 0xb000
	v_lshl_add_u64 v[106:107], v[252:253], 0, s[16:17]
	global_load_lds_dwordx4 v[106:107], off
	v_lshl_add_u64 v[252:253], v[252:253], 0, s[4:5]
	s_mov_b64 s[16:17], 0x1b80080
	s_add_u32 m0, s100, 0x10000
	v_lshl_add_u64 v[106:107], v[254:255], 0, s[16:17]
	global_load_lds_dwordx4 v[106:107], off
	s_mov_b64 s[16:17], 0x1bac080
	s_add_u32 m0, s100, 0x11000
	v_lshl_add_u64 v[106:107], v[254:255], 0, s[16:17]
	global_load_lds_dwordx4 v[106:107], off
	s_mov_b64 s[16:17], 0x1bd8080
	s_add_u32 m0, s100, 0x12000
	v_lshl_add_u64 v[106:107], v[254:255], 0, s[16:17]
	global_load_lds_dwordx4 v[106:107], off
	s_mov_b64 s[16:17], 0x1c04080
	s_add_u32 m0, s100, 0x13000
	v_lshl_add_u64 v[106:107], v[254:255], 0, s[16:17]
	global_load_lds_dwordx4 v[106:107], off
	v_lshl_add_u64 v[254:255], v[254:255], 0, s[4:5]
	s_waitcnt vmcnt(10) lgkmcnt(0)
	s_barrier
	ds_read_b128 v[236:239], v166 offset:49152
	ds_read_b128 v[240:243], v166 offset:53248
	ds_read_b128 v[224:227], v162
	ds_read_b128 v[228:231], v162 offset:4096
	s_mov_b32 s15, 0
